# PEER gather loops (prompt step A and step B): unrolled x2 with swapped register sets, next->current v_mov_b64 copy block removed, vmcnt waits re-derived
# speedup vs baseline: 1.0184x; 1.0184x over previous
; __device__ __forceinline__ f32x2 fp8x2_lo(unsigned w) { return __builtin_amdgcn_cvt_pk_f32_fp8(w, false); }
; __device__ __forceinline__ f32x2 fp8x2_hi(unsigned w) { return __builtin_amdgcn_cvt_pk_f32_fp8(w, true); }
; #define PA_IDS(T) do { const unsigned* kp_ = KP + (size_t)(T) * 256; _Pragma("unroll") for (int qq = 0; qq < 4; ++qq) idv[qq] = *(const u32x4*)(kp_ + 4 * qq); } while (0)
; template <bool NT>
; __device__ __forceinline__ void peer_passA(const Args& a, const PeerWork w) {
;     ...
;     for (;; q += qs) {
;         u32x4 urn[16]; f32x4 hn[4];
;         PA_GATHER(t1, urn, hn);
;         const int t2 = peer_tok(w, min(q + 2 * qs, ql));
;         PA_IDS(t2);
;         float part[16];
; #pragma unroll
;         for (int k = 0; k < 16; ++k) {
;             const unsigned ww[4] = {ur[k].x, ur[k].y, ur[k].z, ur[k].w};
;             f32x2 p2 = {0.f, 0.f};
; #pragma unroll
;             for (int wd = 0; wd < 4; ++wd) { p2 = __builtin_elementwise_fma(fp8x2_lo(ww[wd]), (f32x2){hv[wd][0], hv[wd][1]}, p2); p2 = __builtin_elementwise_fma(fp8x2_hi(ww[wd]), (f32x2){hv[wd][2], hv[wd][3]}, p2); }
;             part[k] = p2[0] + p2[1];
.Lpa_pre_a6:
	s_waitcnt vmcnt(0)
	v_mov_b64_e32 v[182:183], v[4:5]
	v_mov_b64_e32 v[180:181], v[2:3]
	v_mov_b64_e32 v[178:179], v[8:9]
	v_mov_b64_e32 v[176:177], v[6:7]
	v_mov_b64_e32 v[174:175], v[12:13]
	v_mov_b64_e32 v[172:173], v[10:11]
	v_mov_b64_e32 v[170:171], v[16:17]
	v_mov_b64_e32 v[168:169], v[14:15]
	v_mov_b64_e32 v[166:167], v[24:25]
	v_mov_b64_e32 v[164:165], v[22:23]
	v_mov_b64_e32 v[162:163], v[28:29]
	v_mov_b64_e32 v[160:161], v[26:27]
	v_mov_b64_e32 v[152:153], v[36:37]
	v_mov_b64_e32 v[150:151], v[34:35]
	v_mov_b64_e32 v[148:149], v[40:41]
	v_mov_b64_e32 v[146:147], v[38:39]
	v_mov_b64_e32 v[144:145], v[44:45]
	v_mov_b64_e32 v[142:143], v[42:43]
	v_mov_b64_e32 v[140:141], v[48:49]
	v_mov_b64_e32 v[138:139], v[46:47]
	v_mov_b64_e32 v[136:137], v[56:57]
	v_mov_b64_e32 v[134:135], v[54:55]
	v_mov_b64_e32 v[132:133], v[60:61]
	v_mov_b64_e32 v[130:131], v[58:59]
	v_mov_b64_e32 v[128:129], v[68:69]
	v_mov_b64_e32 v[126:127], v[66:67]
	v_mov_b64_e32 v[124:125], v[72:73]
	v_mov_b64_e32 v[116:117], v[80:81]
	v_mov_b64_e32 v[120:121], v[76:77]
	v_mov_b64_e32 v[122:123], v[70:71]
	v_mov_b64_e32 v[114:115], v[78:79]
	v_mov_b64_e32 v[118:119], v[74:75]
.LBB0_1321:
	s_waitcnt vmcnt(24)
	v_cvt_pk_f32_fp8_e32 v[184:185], v180
	v_cvt_pk_f32_fp8_sdwa v[186:187], v180 src0_sel:WORD_1
	v_cvt_pk_f32_fp8_e32 v[188:189], v181
	v_cvt_pk_f32_fp8_sdwa v[180:181], v181 src0_sel:WORD_1
	s_waitcnt vmcnt(5)
	v_pk_fma_f32 v[184:185], v[184:185], v[94:95], 0 op_sel_hi:[1,1,0]
	v_pk_fma_f32 v[184:185], v[186:187], v[96:97], v[184:185]
	v_cvt_pk_f32_fp8_sdwa v[186:187], v182 src0_sel:WORD_1
	v_pk_fma_f32 v[184:185], v[188:189], v[90:91], v[184:185]
	v_cvt_pk_f32_fp8_e32 v[188:189], v183
	v_pk_fma_f32 v[180:181], v[180:181], v[92:93], v[184:185]
	v_cvt_pk_f32_fp8_e32 v[184:185], v182
	v_cvt_pk_f32_fp8_sdwa v[182:183], v183 src0_sel:WORD_1
	v_pk_fma_f32 v[180:181], v[184:185], v[86:87], v[180:181]
	v_cvt_pk_f32_fp8_e32 v[184:185], v177
	v_pk_fma_f32 v[180:181], v[186:187], v[88:89], v[180:181]
	v_pk_fma_f32 v[180:181], v[188:189], v[82:83], v[180:181]
	v_pk_fma_f32 v[180:181], v[182:183], v[84:85], v[180:181]
	v_cvt_pk_f32_fp8_sdwa v[182:183], v176 src0_sel:WORD_1
	v_add_f32_e32 v186, v180, v181
	v_cvt_pk_f32_fp8_e32 v[180:181], v176
	v_cvt_pk_f32_fp8_sdwa v[176:177], v177 src0_sel:WORD_1
	v_pk_fma_f32 v[180:181], v[180:181], v[94:95], 0 op_sel_hi:[1,1,0]
	v_pk_fma_f32 v[180:181], v[182:183], v[96:97], v[180:181]
	v_cvt_pk_f32_fp8_sdwa v[182:183], v178 src0_sel:WORD_1
	v_pk_fma_f32 v[180:181], v[184:185], v[90:91], v[180:181]
	v_cvt_pk_f32_fp8_e32 v[184:185], v179
	v_pk_fma_f32 v[176:177], v[176:177], v[92:93], v[180:181]
	v_cvt_pk_f32_fp8_e32 v[180:181], v178
	v_cvt_pk_f32_fp8_sdwa v[178:179], v179 src0_sel:WORD_1
	v_pk_fma_f32 v[176:177], v[180:181], v[86:87], v[176:177]
	v_cvt_pk_f32_fp8_e32 v[180:181], v173
	v_pk_fma_f32 v[176:177], v[182:183], v[88:89], v[176:177]
	v_pk_fma_f32 v[176:177], v[184:185], v[82:83], v[176:177]
	v_pk_fma_f32 v[176:177], v[178:179], v[84:85], v[176:177]
	v_cvt_pk_f32_fp8_sdwa v[178:179], v172 src0_sel:WORD_1
	v_add_f32_e32 v182, v176, v177
	v_cvt_pk_f32_fp8_e32 v[176:177], v172
	v_cvt_pk_f32_fp8_sdwa v[172:173], v173 src0_sel:WORD_1
	v_pk_fma_f32 v[176:177], v[176:177], v[94:95], 0 op_sel_hi:[1,1,0]
	v_pk_fma_f32 v[176:177], v[178:179], v[96:97], v[176:177]
	v_cvt_pk_f32_fp8_sdwa v[178:179], v174 src0_sel:WORD_1
	v_pk_fma_f32 v[176:177], v[180:181], v[90:91], v[176:177]
	v_cvt_pk_f32_fp8_e32 v[180:181], v175
	v_pk_fma_f32 v[172:173], v[172:173], v[92:93], v[176:177]
	v_cvt_pk_f32_fp8_e32 v[176:177], v174
	v_cvt_pk_f32_fp8_sdwa v[174:175], v175 src0_sel:WORD_1
	v_pk_fma_f32 v[172:173], v[176:177], v[86:87], v[172:173]
	v_cvt_pk_f32_fp8_e32 v[176:177], v169
	v_pk_fma_f32 v[172:173], v[178:179], v[88:89], v[172:173]
	v_pk_fma_f32 v[172:173], v[180:181], v[82:83], v[172:173]
	v_pk_fma_f32 v[172:173], v[174:175], v[84:85], v[172:173]
	v_cvt_pk_f32_fp8_sdwa v[174:175], v168 src0_sel:WORD_1
	v_add_f32_e32 v178, v172, v173
	v_cvt_pk_f32_fp8_e32 v[172:173], v168
	v_cvt_pk_f32_fp8_sdwa v[168:169], v169 src0_sel:WORD_1
	v_pk_fma_f32 v[172:173], v[172:173], v[94:95], 0 op_sel_hi:[1,1,0]
	v_pk_fma_f32 v[172:173], v[174:175], v[96:97], v[172:173]
	v_cvt_pk_f32_fp8_sdwa v[174:175], v170 src0_sel:WORD_1
	v_pk_fma_f32 v[172:173], v[176:177], v[90:91], v[172:173]
	v_cvt_pk_f32_fp8_e32 v[176:177], v171
	v_pk_fma_f32 v[168:169], v[168:169], v[92:93], v[172:173]
	v_cvt_pk_f32_fp8_e32 v[172:173], v170
	v_cvt_pk_f32_fp8_sdwa v[170:171], v171 src0_sel:WORD_1
	s_waitcnt vmcnt(1)
; __device__ __forceinline__ f32x2 fp8x2_lo(unsigned w) { return __builtin_amdgcn_cvt_pk_f32_fp8(w, false); }
; __device__ __forceinline__ f32x2 fp8x2_hi(unsigned w) { return __builtin_amdgcn_cvt_pk_f32_fp8(w, true); }
; #define PA_IDS(T) do { const unsigned* kp_ = KP + (size_t)(T) * 256; _Pragma("unroll") for (int qq = 0; qq < 4; ++qq) idv[qq] = *(const u32x4*)(kp_ + 4 * qq); } while (0)
; template <bool NT>
; __device__ __forceinline__ void peer_passA(const Args& a, const PeerWork w) {
;     ...
;     int t = peer_tok(w, q), t1 = peer_tok(w, min(q + qs, ql));
;     PA_IDS(t);
;     PA_GATHER(t, ur, hv);
;     PA_IDS(t1);
; #pragma unroll 1
;     for (;; q += qs) {
;         u32x4 urn[16]; f32x4 hn[4];
;         PA_GATHER(t1, urn, hn);
;         const int t2 = peer_tok(w, min(q + 2 * qs, ql));
;         PA_IDS(t2);
;         float part[16];
; #pragma unroll
;         for (int k = 0; k < 16; ++k) {
;             const unsigned ww[4] = {ur[k].x, ur[k].y, ur[k].z, ur[k].w};
;             f32x2 p2 = {0.f, 0.f};
; #pragma unroll
;             for (int wd = 0; wd < 4; ++wd) { p2 = __builtin_elementwise_fma(fp8x2_lo(ww[wd]), (f32x2){hv[wd][0], hv[wd][1]}, p2); p2 = __builtin_elementwise_fma(fp8x2_hi(ww[wd]), (f32x2){hv[wd][2], hv[wd][3]}, p2); }
;             part[k] = p2[0] + p2[1];
	v_lshl_or_b32 v10, v30, 7, v1
	v_pk_fma_f32 v[168:169], v[172:173], v[86:87], v[168:169]
	v_cvt_pk_f32_fp8_e32 v[172:173], v165
	v_pk_fma_f32 v[168:169], v[174:175], v[88:89], v[168:169]
	v_lshl_or_b32 v11, v31, 7, v1
	v_pk_fma_f32 v[168:169], v[176:177], v[82:83], v[168:169]
	v_lshl_or_b32 v22, v32, 7, v1
	v_pk_fma_f32 v[168:169], v[170:171], v[84:85], v[168:169]
	v_cvt_pk_f32_fp8_sdwa v[170:171], v164 src0_sel:WORD_1
	v_add_f32_e32 v174, v168, v169
	v_cvt_pk_f32_fp8_e32 v[168:169], v164
	v_cvt_pk_f32_fp8_sdwa v[164:165], v165 src0_sel:WORD_1
	v_lshl_or_b32 v23, v33, 7, v1
	v_lshl_or_b32 v18, v18, 7, v1
	v_pk_fma_f32 v[168:169], v[168:169], v[94:95], 0 op_sel_hi:[1,1,0]
	v_lshl_or_b32 v19, v19, 7, v1
	v_pk_fma_f32 v[168:169], v[170:171], v[96:97], v[168:169]
	v_cvt_pk_f32_fp8_sdwa v[170:171], v166 src0_sel:WORD_1
	v_pk_fma_f32 v[168:169], v[172:173], v[90:91], v[168:169]
	v_cvt_pk_f32_fp8_e32 v[172:173], v167
	v_pk_fma_f32 v[164:165], v[164:165], v[92:93], v[168:169]
	v_cvt_pk_f32_fp8_e32 v[168:169], v166
	v_cvt_pk_f32_fp8_sdwa v[166:167], v167 src0_sel:WORD_1
	global_load_dwordx4 v[2:5], v10, s[10:11]
	global_load_dwordx4 v[6:9], v11, s[10:11]
	v_pk_fma_f32 v[164:165], v[168:169], v[86:87], v[164:165]
	v_cvt_pk_f32_fp8_e32 v[168:169], v161
	v_pk_fma_f32 v[164:165], v[170:171], v[88:89], v[164:165]
	global_load_dwordx4 v[10:13], v22, s[10:11]
	global_load_dwordx4 v[14:17], v23, s[10:11]
	v_pk_fma_f32 v[164:165], v[172:173], v[82:83], v[164:165]
	global_load_dwordx4 v[22:25], v18, s[10:11]
	global_load_dwordx4 v[26:29], v19, s[10:11]
	v_pk_fma_f32 v[164:165], v[166:167], v[84:85], v[164:165]
	v_cvt_pk_f32_fp8_sdwa v[166:167], v160 src0_sel:WORD_1
	v_add_f32_e32 v170, v164, v165
	v_cvt_pk_f32_fp8_e32 v[164:165], v160
	v_cvt_pk_f32_fp8_sdwa v[160:161], v161 src0_sel:WORD_1
	v_lshl_or_b32 v18, v20, 7, v1
	v_lshl_or_b32 v19, v21, 7, v1
	v_pk_fma_f32 v[164:165], v[164:165], v[94:95], 0 op_sel_hi:[1,1,0]
	global_load_dwordx4 v[34:37], v18, s[10:11]
	global_load_dwordx4 v[38:41], v19, s[10:11]
	v_pk_fma_f32 v[164:165], v[166:167], v[96:97], v[164:165]
	v_cvt_pk_f32_fp8_sdwa v[166:167], v162 src0_sel:WORD_1
	v_pk_fma_f32 v[164:165], v[168:169], v[90:91], v[164:165]
	v_cvt_pk_f32_fp8_e32 v[168:169], v163
	v_pk_fma_f32 v[160:161], v[160:161], v[92:93], v[164:165]
	v_cvt_pk_f32_fp8_e32 v[164:165], v162
	v_cvt_pk_f32_fp8_sdwa v[162:163], v163 src0_sel:WORD_1
	v_lshl_or_b32 v18, v62, 7, v1
	v_lshl_or_b32 v19, v63, 7, v1
	v_pk_fma_f32 v[160:161], v[164:165], v[86:87], v[160:161]
	v_cvt_pk_f32_fp8_e32 v[164:165], v151
	v_pk_fma_f32 v[160:161], v[166:167], v[88:89], v[160:161]
	global_load_dwordx4 v[42:45], v18, s[10:11]
	global_load_dwordx4 v[46:49], v19, s[10:11]
	v_pk_fma_f32 v[160:161], v[168:169], v[82:83], v[160:161]
	v_lshl_or_b32 v18, v64, 7, v1
	v_pk_fma_f32 v[160:161], v[162:163], v[84:85], v[160:161]
	v_cvt_pk_f32_fp8_sdwa v[162:163], v150 src0_sel:WORD_1
	v_add_f32_e32 v166, v160, v161
	v_cvt_pk_f32_fp8_e32 v[160:161], v150
	v_cvt_pk_f32_fp8_sdwa v[150:151], v151 src0_sel:WORD_1
	v_lshl_or_b32 v19, v65, 7, v1
	s_mov_b32 s18, s16
	v_pk_fma_f32 v[160:161], v[160:161], v[94:95], 0 op_sel_hi:[1,1,0]
	s_mov_b32 s16, s14
	v_pk_fma_f32 v[160:161], v[162:163], v[96:97], v[160:161]
	v_cvt_pk_f32_fp8_sdwa v[162:163], v152 src0_sel:WORD_1
	v_pk_fma_f32 v[160:161], v[164:165], v[90:91], v[160:161]
	v_cvt_pk_f32_fp8_e32 v[164:165], v153
	v_pk_fma_f32 v[150:151], v[150:151], v[92:93], v[160:161]
	v_cvt_pk_f32_fp8_e32 v[160:161], v152
	v_cvt_pk_f32_fp8_sdwa v[152:153], v153 src0_sel:WORD_1
	global_load_dwordx4 v[54:57], v18, s[10:11]
	global_load_dwordx4 v[58:61], v19, s[10:11]
	v_pk_fma_f32 v[150:151], v[160:161], v[86:87], v[150:151]
	v_cvt_pk_f32_fp8_e32 v[160:161], v147
	v_pk_fma_f32 v[150:151], v[162:163], v[88:89], v[150:151]
	v_lshl_or_b32 v18, v50, 7, v1
	v_pk_fma_f32 v[150:151], v[164:165], v[82:83], v[150:151]
	v_lshl_or_b32 v19, v51, 7, v1
	v_pk_fma_f32 v[150:151], v[152:153], v[84:85], v[150:151]
	v_cvt_pk_f32_fp8_sdwa v[152:153], v146 src0_sel:WORD_1
	v_add_f32_e32 v162, v150, v151
	v_cvt_pk_f32_fp8_e32 v[150:151], v146
	v_cvt_pk_f32_fp8_sdwa v[146:147], v147 src0_sel:WORD_1
	s_ashr_i32 s17, s14, 31
	v_pk_fma_f32 v[150:151], v[150:151], v[94:95], 0 op_sel_hi:[1,1,0]
	v_pk_fma_f32 v[150:151], v[152:153], v[96:97], v[150:151]
	v_cvt_pk_f32_fp8_sdwa v[152:153], v148 src0_sel:WORD_1
	v_pk_fma_f32 v[150:151], v[160:161], v[90:91], v[150:151]
	v_cvt_pk_f32_fp8_e32 v[160:161], v149
	v_pk_fma_f32 v[146:147], v[146:147], v[92:93], v[150:151]
	v_cvt_pk_f32_fp8_e32 v[150:151], v148
	v_cvt_pk_f32_fp8_sdwa v[148:149], v149 src0_sel:WORD_1
	global_load_dwordx4 v[66:69], v18, s[10:11]
	global_load_dwordx4 v[70:73], v19, s[10:11]
	v_pk_fma_f32 v[146:147], v[150:151], v[86:87], v[146:147]
	v_cvt_pk_f32_fp8_e32 v[150:151], v143
	v_pk_fma_f32 v[146:147], v[152:153], v[88:89], v[146:147]
	v_lshl_or_b32 v18, v52, 7, v1
	v_pk_fma_f32 v[146:147], v[160:161], v[82:83], v[146:147]
	v_lshl_or_b32 v19, v53, 7, v1
	v_pk_fma_f32 v[146:147], v[148:149], v[84:85], v[146:147]
	v_cvt_pk_f32_fp8_sdwa v[148:149], v142 src0_sel:WORD_1
	v_add_f32_e32 v152, v146, v147
	v_cvt_pk_f32_fp8_e32 v[146:147], v142
	v_cvt_pk_f32_fp8_sdwa v[142:143], v143 src0_sel:WORD_1
	s_lshl_b64 s[14:15], s[16:17], 12
	s_add_i32 s17, s12, s13
	v_pk_fma_f32 v[146:147], v[146:147], v[94:95], 0 op_sel_hi:[1,1,0]
	v_pk_fma_f32 v[146:147], v[148:149], v[96:97], v[146:147]
	v_cvt_pk_f32_fp8_sdwa v[148:149], v144 src0_sel:WORD_1
	v_pk_fma_f32 v[146:147], v[150:151], v[90:91], v[146:147]
	v_cvt_pk_f32_fp8_e32 v[150:151], v145
	v_pk_fma_f32 v[142:143], v[142:143], v[92:93], v[146:147]
	v_cvt_pk_f32_fp8_e32 v[146:147], v144
; __device__ __forceinline__ f32x2 fp8x2_lo(unsigned w) { return __builtin_amdgcn_cvt_pk_f32_fp8(w, false); }
; __device__ __forceinline__ f32x2 fp8x2_hi(unsigned w) { return __builtin_amdgcn_cvt_pk_f32_fp8(w, true); }
; #define PA_IDS(T) do { const unsigned* kp_ = KP + (size_t)(T) * 256; _Pragma("unroll") for (int qq = 0; qq < 4; ++qq) idv[qq] = *(const u32x4*)(kp_ + 4 * qq); } while (0)
; template <bool NT>
; __device__ __forceinline__ void peer_passA(const Args& a, const PeerWork w) {
;     ...
;     int t = peer_tok(w, q), t1 = peer_tok(w, min(q + qs, ql));
;     PA_IDS(t);
;     PA_GATHER(t, ur, hv);
;     PA_IDS(t1);
; #pragma unroll 1
;     for (;; q += qs) {
;         u32x4 urn[16]; f32x4 hn[4];
;         PA_GATHER(t1, urn, hn);
;         const int t2 = peer_tok(w, min(q + 2 * qs, ql));
;         PA_IDS(t2);
;         float part[16];
; #pragma unroll
;         for (int k = 0; k < 16; ++k) {
;             const unsigned ww[4] = {ur[k].x, ur[k].y, ur[k].z, ur[k].w};
;             f32x2 p2 = {0.f, 0.f};
; #pragma unroll
;             for (int wd = 0; wd < 4; ++wd) { p2 = __builtin_elementwise_fma(fp8x2_lo(ww[wd]), (f32x2){hv[wd][0], hv[wd][1]}, p2); p2 = __builtin_elementwise_fma(fp8x2_hi(ww[wd]), (f32x2){hv[wd][2], hv[wd][3]}, p2); }
;             part[k] = p2[0] + p2[1];
	v_cvt_pk_f32_fp8_sdwa v[144:145], v145 src0_sel:WORD_1
	global_load_dwordx4 v[74:77], v18, s[10:11]
	global_load_dwordx4 v[78:81], v19, s[10:11]
	v_pk_fma_f32 v[142:143], v[146:147], v[86:87], v[142:143]
	v_cvt_pk_f32_fp8_e32 v[146:147], v139
	v_pk_fma_f32 v[142:143], v[148:149], v[88:89], v[142:143]
	v_lshl_add_u64 v[18:19], v[156:157], 0, s[14:15]
	v_pk_fma_f32 v[142:143], v[150:151], v[82:83], v[142:143]
	s_min_i32 s14, s17, 0x3fff
	v_pk_fma_f32 v[142:143], v[144:145], v[84:85], v[142:143]
	v_cvt_pk_f32_fp8_sdwa v[144:145], v138 src0_sel:WORD_1
	v_add_f32_e32 v148, v142, v143
	v_cvt_pk_f32_fp8_e32 v[142:143], v138
	v_cvt_pk_f32_fp8_sdwa v[138:139], v139 src0_sel:WORD_1
	s_ashr_i32 s15, s14, 31
	s_lshl_b64 s[28:29], s[14:15], 10
	v_pk_fma_f32 v[142:143], v[142:143], v[94:95], 0 op_sel_hi:[1,1,0]
	v_lshl_add_u64 v[30:31], v[154:155], 0, s[28:29]
	v_pk_fma_f32 v[142:143], v[144:145], v[96:97], v[142:143]
	v_cvt_pk_f32_fp8_sdwa v[144:145], v140 src0_sel:WORD_1
	v_pk_fma_f32 v[142:143], v[146:147], v[90:91], v[142:143]
	v_cvt_pk_f32_fp8_e32 v[146:147], v141
	v_pk_fma_f32 v[138:139], v[138:139], v[92:93], v[142:143]
	v_cvt_pk_f32_fp8_e32 v[142:143], v140
	v_cvt_pk_f32_fp8_sdwa v[140:141], v141 src0_sel:WORD_1
	global_load_dwordx4 v[110:113], v[18:19], off offset:48
	global_load_dwordx4 v[106:109], v[18:19], off offset:32
	global_load_dwordx4 v[102:105], v[18:19], off offset:16
	global_load_dwordx4 v[98:101], v[18:19], off
	global_load_dwordx4 v[50:53], v[30:31], off offset:48
	global_load_dwordx4 v[62:65], v[30:31], off offset:32
	s_nop 0
	global_load_dwordx4 v[18:21], v[30:31], off offset:16
	s_nop 0
	global_load_dwordx4 v[30:33], v[30:31], off
	v_pk_fma_f32 v[138:139], v[142:143], v[86:87], v[138:139]
	v_cvt_pk_f32_fp8_e32 v[142:143], v135
	v_pk_fma_f32 v[138:139], v[144:145], v[88:89], v[138:139]
	s_ashr_i32 s19, s18, 31
	v_pk_fma_f32 v[138:139], v[146:147], v[82:83], v[138:139]
	s_lshl_b64 s[18:19], s[18:19], 11
	v_pk_fma_f32 v[138:139], v[140:141], v[84:85], v[138:139]
	v_cvt_pk_f32_fp8_sdwa v[140:141], v134 src0_sel:WORD_1
	v_add_f32_e32 v144, v138, v139
	v_cvt_pk_f32_fp8_e32 v[138:139], v134
	v_cvt_pk_f32_fp8_sdwa v[134:135], v135 src0_sel:WORD_1
	s_add_i32 s12, s22, s12
	s_cmpk_gt_i32 s12, 0x3fff
	v_pk_fma_f32 v[138:139], v[138:139], v[94:95], 0 op_sel_hi:[1,1,0]
	v_readfirstlane_b32 s12, v0
	v_pk_fma_f32 v[138:139], v[140:141], v[96:97], v[138:139]
	v_cvt_pk_f32_fp8_sdwa v[140:141], v136 src0_sel:WORD_1
	v_pk_fma_f32 v[138:139], v[142:143], v[90:91], v[138:139]
	v_cvt_pk_f32_fp8_e32 v[142:143], v137
	v_pk_fma_f32 v[134:135], v[134:135], v[92:93], v[138:139]
	v_cvt_pk_f32_fp8_e32 v[138:139], v136
	v_cvt_pk_f32_fp8_sdwa v[136:137], v137 src0_sel:WORD_1
	v_pk_fma_f32 v[134:135], v[138:139], v[86:87], v[134:135]
	s_nop 0
	v_pk_fma_f32 v[134:135], v[140:141], v[88:89], v[134:135]
	v_cvt_pk_f32_fp8_e32 v[138:139], v131
	v_pk_fma_f32 v[134:135], v[142:143], v[82:83], v[134:135]
	s_nop 0
	v_pk_fma_f32 v[134:135], v[136:137], v[84:85], v[134:135]
	v_cvt_pk_f32_fp8_sdwa v[136:137], v130 src0_sel:WORD_1
	v_add_f32_e32 v140, v134, v135
	v_cvt_pk_f32_fp8_e32 v[134:135], v130
	v_cvt_pk_f32_fp8_sdwa v[130:131], v131 src0_sel:WORD_1
	v_pk_fma_f32 v[134:135], v[134:135], v[94:95], 0 op_sel_hi:[1,1,0]
	s_nop 0
	v_pk_fma_f32 v[134:135], v[136:137], v[96:97], v[134:135]
	v_cvt_pk_f32_fp8_sdwa v[136:137], v132 src0_sel:WORD_1
	v_pk_fma_f32 v[134:135], v[138:139], v[90:91], v[134:135]
	v_cvt_pk_f32_fp8_e32 v[138:139], v133
	v_pk_fma_f32 v[130:131], v[130:131], v[92:93], v[134:135]
	v_cvt_pk_f32_fp8_e32 v[134:135], v132
	v_cvt_pk_f32_fp8_sdwa v[132:133], v133 src0_sel:WORD_1
	v_pk_fma_f32 v[130:131], v[134:135], v[86:87], v[130:131]
	s_nop 0
	v_pk_fma_f32 v[130:131], v[136:137], v[88:89], v[130:131]
	v_cvt_pk_f32_fp8_e32 v[134:135], v127
	v_pk_fma_f32 v[130:131], v[138:139], v[82:83], v[130:131]
	s_nop 0
	v_pk_fma_f32 v[130:131], v[132:133], v[84:85], v[130:131]
	v_cvt_pk_f32_fp8_sdwa v[132:133], v126 src0_sel:WORD_1
	v_add_f32_e32 v136, v130, v131
	v_cvt_pk_f32_fp8_e32 v[130:131], v126
	v_cvt_pk_f32_fp8_sdwa v[126:127], v127 src0_sel:WORD_1
	v_pk_fma_f32 v[130:131], v[130:131], v[94:95], 0 op_sel_hi:[1,1,0]
	s_nop 0
	v_pk_fma_f32 v[130:131], v[132:133], v[96:97], v[130:131]
	v_cvt_pk_f32_fp8_sdwa v[132:133], v128 src0_sel:WORD_1
	v_pk_fma_f32 v[130:131], v[134:135], v[90:91], v[130:131]
	v_cvt_pk_f32_fp8_e32 v[134:135], v129
	v_pk_fma_f32 v[126:127], v[126:127], v[92:93], v[130:131]
	v_cvt_pk_f32_fp8_e32 v[130:131], v128
	v_cvt_pk_f32_fp8_sdwa v[128:129], v129 src0_sel:WORD_1
	v_pk_fma_f32 v[126:127], v[130:131], v[86:87], v[126:127]
	s_nop 0
	v_pk_fma_f32 v[126:127], v[132:133], v[88:89], v[126:127]
	v_cvt_pk_f32_fp8_e32 v[130:131], v123
	v_pk_fma_f32 v[126:127], v[134:135], v[82:83], v[126:127]
	s_nop 0
	v_pk_fma_f32 v[126:127], v[128:129], v[84:85], v[126:127]
	v_cvt_pk_f32_fp8_sdwa v[128:129], v122 src0_sel:WORD_1
	v_add_f32_e32 v132, v126, v127
	v_cvt_pk_f32_fp8_e32 v[126:127], v122
	v_cvt_pk_f32_fp8_sdwa v[122:123], v123 src0_sel:WORD_1
	v_pk_fma_f32 v[126:127], v[126:127], v[94:95], 0 op_sel_hi:[1,1,0]
	s_nop 0
	v_pk_fma_f32 v[126:127], v[128:129], v[96:97], v[126:127]
	v_cvt_pk_f32_fp8_sdwa v[128:129], v124 src0_sel:WORD_1
	v_pk_fma_f32 v[126:127], v[130:131], v[90:91], v[126:127]
	v_cvt_pk_f32_fp8_e32 v[130:131], v125
	v_pk_fma_f32 v[122:123], v[122:123], v[92:93], v[126:127]
	v_cvt_pk_f32_fp8_e32 v[126:127], v124
	v_cvt_pk_f32_fp8_sdwa v[124:125], v125 src0_sel:WORD_1
	v_pk_fma_f32 v[122:123], v[126:127], v[86:87], v[122:123]
	s_nop 0
	v_pk_fma_f32 v[122:123], v[128:129], v[88:89], v[122:123]
	v_cvt_pk_f32_fp8_e32 v[126:127], v119
; __device__ __forceinline__ unsigned cvt_pk_bf16(float lo, float hi) { unsigned r; asm volatile("v_cvt_pk_bf16_f32 %0, %1, %2" : "=v"(r) : "v"(lo), "v"(hi)); return r; }
; template <int CTRL> __device__ __forceinline__ float dpp_f(float x) { return __uint_as_float((unsigned)__builtin_amdgcn_update_dpp(0, (int)__float_as_uint(x), CTRL, 0xf, 0xf, false)); }
; __device__ __forceinline__ float xor4_f(float x) { float r = dpp_bank_f<0x104, 0x5>(0.f, x); return dpp_bank_f<0x114, 0xa>(r, x); }
; template <bool NT>
; __device__ __forceinline__ void peer_passA(const Args& a, const PeerWork w) {
;     ...
;         float w8[8], w4[4], w2[2];
;         { const bool up = (lane & 4) != 0;
; #pragma unroll
;           for (int m = 0; m < 8; ++m) { const float keep = up ? part[m + 8] : part[m], send = up ? part[m] : part[m + 8]; w8[m] = keep + xor4_f(send); } }
;         { const bool up = (lane & 2) != 0;
; #pragma unroll
;           for (int m = 0; m < 4; ++m) { const float keep = up ? w8[m + 4] : w8[m], send = up ? w8[m] : w8[m + 4]; w4[m] = keep + dpp_f<0x4E>(send); } }
;         { const bool up = (lane & 1) != 0;
; #pragma unroll
;           for (int m = 0; m < 2; ++m) { const float keep = up ? w4[m + 2] : w4[m], send = up ? w4[m] : w4[m + 2]; w2[m] = keep + dpp_f<0xB1>(send); } }
;         PD[(size_t)t * 512] = cvt_pk_bf16(w2[0], w2[1]);
;         if (q + qs > ql) break;
	v_pk_fma_f32 v[122:123], v[130:131], v[82:83], v[122:123]
	s_nop 0
	v_pk_fma_f32 v[122:123], v[124:125], v[84:85], v[122:123]
	v_cvt_pk_f32_fp8_sdwa v[124:125], v118 src0_sel:WORD_1
	v_add_f32_e32 v128, v122, v123
	v_cvt_pk_f32_fp8_e32 v[122:123], v118
	v_cvt_pk_f32_fp8_sdwa v[118:119], v119 src0_sel:WORD_1
	v_pk_fma_f32 v[122:123], v[122:123], v[94:95], 0 op_sel_hi:[1,1,0]
	s_nop 0
	v_pk_fma_f32 v[122:123], v[124:125], v[96:97], v[122:123]
	v_cvt_pk_f32_fp8_sdwa v[124:125], v120 src0_sel:WORD_1
	v_pk_fma_f32 v[122:123], v[126:127], v[90:91], v[122:123]
	v_cvt_pk_f32_fp8_e32 v[126:127], v121
	v_pk_fma_f32 v[118:119], v[118:119], v[92:93], v[122:123]
	v_cvt_pk_f32_fp8_e32 v[122:123], v120
	v_cvt_pk_f32_fp8_sdwa v[120:121], v121 src0_sel:WORD_1
	v_pk_fma_f32 v[118:119], v[122:123], v[86:87], v[118:119]
	s_nop 0
	v_pk_fma_f32 v[118:119], v[124:125], v[88:89], v[118:119]
	v_cvt_pk_f32_fp8_e32 v[122:123], v115
	v_pk_fma_f32 v[118:119], v[126:127], v[82:83], v[118:119]
	s_nop 0
	v_pk_fma_f32 v[118:119], v[120:121], v[84:85], v[118:119]
	v_cvt_pk_f32_fp8_sdwa v[120:121], v114 src0_sel:WORD_1
	v_add_f32_e32 v124, v118, v119
	v_cvt_pk_f32_fp8_e32 v[118:119], v114
	v_cvt_pk_f32_fp8_sdwa v[114:115], v115 src0_sel:WORD_1
	v_pk_fma_f32 v[94:95], v[118:119], v[94:95], 0 op_sel_hi:[1,1,0]
	s_nop 0
	v_pk_fma_f32 v[94:95], v[120:121], v[96:97], v[94:95]
	v_cvt_pk_f32_fp8_e32 v[96:97], v117
	v_pk_fma_f32 v[90:91], v[122:123], v[90:91], v[94:95]
	v_cvt_pk_f32_fp8_sdwa v[94:95], v116 src0_sel:WORD_1
	v_pk_fma_f32 v[90:91], v[114:115], v[92:93], v[90:91]
	v_cvt_pk_f32_fp8_e32 v[92:93], v116
	v_cvt_pk_f32_fp8_sdwa v[114:115], v117 src0_sel:WORD_1
	v_pk_fma_f32 v[86:87], v[92:93], v[86:87], v[90:91]
	s_nop 0
	v_pk_fma_f32 v[86:87], v[94:95], v[88:89], v[86:87]
	v_mov_b32_e32 v88, 0
	v_pk_fma_f32 v[82:83], v[96:97], v[82:83], v[86:87]
	v_mov_b32_e32 v86, 0
	v_pk_fma_f32 v[82:83], v[114:115], v[84:85], v[82:83]
	v_cndmask_b32_e64 v84, v186, v148, s[0:1]
	v_mov_b32_e32 v85, 0
	v_add_f32_e32 v82, v82, v83
	v_cndmask_b32_e64 v83, v148, v186, s[0:1]
	v_mov_b32_dpp v85, v84 row_shl:4 row_mask:0xf bank_mask:0x5
	v_mov_b32_e32 v87, 0
	v_mov_b32_e32 v89, 0
	v_mov_b32_dpp v85, v84 row_shr:4 row_mask:0xf bank_mask:0xa
	v_add_f32_e32 v83, v83, v85
	v_cndmask_b32_e64 v85, v182, v144, s[0:1]
	v_cndmask_b32_e64 v84, v144, v182, s[0:1]
	v_mov_b32_e32 v90, 0
	v_mov_b32_dpp v86, v85 row_shl:4 row_mask:0xf bank_mask:0x5
	v_mov_b32_e32 v91, 0
	s_nop 0
	v_mov_b32_dpp v86, v85 row_shr:4 row_mask:0xf bank_mask:0xa
	v_add_f32_e32 v84, v84, v86
	v_cndmask_b32_e64 v86, v178, v140, s[0:1]
	v_cndmask_b32_e64 v85, v140, v178, s[0:1]
	s_nop 0
	v_mov_b32_dpp v87, v86 row_shl:4 row_mask:0xf bank_mask:0x5
	s_nop 1
	v_mov_b32_dpp v87, v86 row_shr:4 row_mask:0xf bank_mask:0xa
	v_add_f32_e32 v85, v85, v87
	v_cndmask_b32_e64 v87, v174, v136, s[0:1]
	v_cndmask_b32_e64 v86, v136, v174, s[0:1]
	s_nop 0
	v_mov_b32_dpp v88, v87 row_shl:4 row_mask:0xf bank_mask:0x5
	s_nop 1
	v_mov_b32_dpp v88, v87 row_shr:4 row_mask:0xf bank_mask:0xa
	v_add_f32_e32 v86, v86, v88
	v_cndmask_b32_e64 v88, v170, v132, s[0:1]
	v_cndmask_b32_e64 v87, v132, v170, s[0:1]
	s_nop 0
	v_mov_b32_dpp v89, v88 row_shl:4 row_mask:0xf bank_mask:0x5
	s_nop 1
	v_mov_b32_dpp v89, v88 row_shr:4 row_mask:0xf bank_mask:0xa
	v_add_f32_e32 v87, v87, v89
	v_cndmask_b32_e64 v89, v166, v128, s[0:1]
	v_cndmask_b32_e64 v88, v128, v166, s[0:1]
	s_nop 0
	v_mov_b32_dpp v90, v89 row_shl:4 row_mask:0xf bank_mask:0x5
	s_nop 1
	v_mov_b32_dpp v90, v89 row_shr:4 row_mask:0xf bank_mask:0xa
	v_add_f32_e32 v88, v88, v90
	v_cndmask_b32_e64 v90, v162, v124, s[0:1]
	v_cndmask_b32_e64 v89, v124, v162, s[0:1]
	s_nop 0
	v_mov_b32_dpp v91, v90 row_shl:4 row_mask:0xf bank_mask:0x5
	s_nop 1
	v_mov_b32_dpp v91, v90 row_shr:4 row_mask:0xf bank_mask:0xa
	v_add_f32_e32 v89, v89, v91
	v_cndmask_b32_e64 v90, v82, v152, s[0:1]
	v_cndmask_b32_e64 v82, v152, v82, s[0:1]
	v_mov_b32_e32 v91, 0
	s_nop 1
	v_mov_b32_dpp v91, v82 row_shl:4 row_mask:0xf bank_mask:0x5
	s_nop 1
	v_mov_b32_dpp v91, v82 row_shr:4 row_mask:0xf bank_mask:0xa
	v_add_f32_e32 v82, v90, v91
	v_cndmask_b32_e64 v90, v87, v83, s[4:5]
	v_cndmask_b32_e64 v83, v83, v87, s[4:5]
	v_cndmask_b32_e64 v87, v88, v84, s[4:5]
	v_cndmask_b32_e64 v84, v84, v88, s[4:5]
	v_add_f32_dpp v83, v83, v90 quad_perm:[2,3,0,1] row_mask:0xf bank_mask:0xf bound_ctrl:1
	s_nop 0
	v_add_f32_dpp v84, v84, v87 quad_perm:[2,3,0,1] row_mask:0xf bank_mask:0xf bound_ctrl:1
	v_cndmask_b32_e64 v87, v89, v85, s[4:5]
	v_cndmask_b32_e64 v85, v85, v89, s[4:5]
	s_nop 1
	v_add_f32_dpp v85, v85, v87 quad_perm:[2,3,0,1] row_mask:0xf bank_mask:0xf bound_ctrl:1
	v_cndmask_b32_e64 v87, v82, v86, s[4:5]
	v_cndmask_b32_e64 v82, v86, v82, s[4:5]
	v_cndmask_b32_e64 v86, v85, v83, s[6:7]
	v_cndmask_b32_e64 v83, v83, v85, s[6:7]
	v_add_f32_dpp v82, v82, v87 quad_perm:[2,3,0,1] row_mask:0xf bank_mask:0xf bound_ctrl:1
	v_cndmask_b32_e64 v85, v82, v84, s[6:7]
	v_cndmask_b32_e64 v82, v84, v82, s[6:7]
	v_add_f32_dpp v83, v83, v86 quad_perm:[1,0,3,2] row_mask:0xf bank_mask:0xf bound_ctrl:1
	s_nop 0
	v_add_f32_dpp v82, v82, v85 quad_perm:[1,0,3,2] row_mask:0xf bank_mask:0xf bound_ctrl:1
	v_cvt_pk_bf16_f32 v84, v83, v82
	v_lshl_add_u64 v[82:83], v[158:159], 0, s[18:19]
	s_mov_b64 s[18:19], -1
	global_store_dword v[82:83], v84, off
	s_cbranch_scc1 .LBB0_1323
; __device__ __forceinline__ f32x2 fp8x2_lo(unsigned w) { return __builtin_amdgcn_cvt_pk_f32_fp8(w, false); }
; __device__ __forceinline__ f32x2 fp8x2_hi(unsigned w) { return __builtin_amdgcn_cvt_pk_f32_fp8(w, true); }
; #define PA_IDS(T) do { const unsigned* kp_ = KP + (size_t)(T) * 256; _Pragma("unroll") for (int qq = 0; qq < 4; ++qq) idv[qq] = *(const u32x4*)(kp_ + 4 * qq); } while (0)
; template <bool NT>
; __device__ __forceinline__ void peer_passA(const Args& a, const PeerWork w) {
;     ...
;     for (;; q += qs) {
;         u32x4 urn[16]; f32x4 hn[4];
;         PA_GATHER(t1, urn, hn);
;         const int t2 = peer_tok(w, min(q + 2 * qs, ql));
;         PA_IDS(t2);
;         float part[16];
; #pragma unroll
;         for (int k = 0; k < 16; ++k) {
;             const unsigned ww[4] = {ur[k].x, ur[k].y, ur[k].z, ur[k].w};
;             f32x2 p2 = {0.f, 0.f};
; #pragma unroll
;             for (int wd = 0; wd < 4; ++wd) { p2 = __builtin_elementwise_fma(fp8x2_lo(ww[wd]), (f32x2){hv[wd][0], hv[wd][1]}, p2); p2 = __builtin_elementwise_fma(fp8x2_hi(ww[wd]), (f32x2){hv[wd][2], hv[wd][3]}, p2); }
;             part[k] = p2[0] + p2[1];
	s_sub_i32 s12, s17, s22
	s_mov_b64 s[18:19], 0
	s_waitcnt vmcnt(24)
	v_cvt_pk_f32_fp8_e32 v[184:185], v2
	v_cvt_pk_f32_fp8_sdwa v[186:187], v2 src0_sel:WORD_1
	v_cvt_pk_f32_fp8_e32 v[188:189], v3
	v_cvt_pk_f32_fp8_sdwa v[2:3], v3 src0_sel:WORD_1
	s_waitcnt vmcnt(5)
	v_pk_fma_f32 v[184:185], v[184:185], v[98:99], 0 op_sel_hi:[1,1,0]
	v_pk_fma_f32 v[184:185], v[186:187], v[100:101], v[184:185]
	v_cvt_pk_f32_fp8_sdwa v[186:187], v4 src0_sel:WORD_1
	v_pk_fma_f32 v[184:185], v[188:189], v[102:103], v[184:185]
	v_cvt_pk_f32_fp8_e32 v[188:189], v5
	v_pk_fma_f32 v[2:3], v[2:3], v[104:105], v[184:185]
	v_cvt_pk_f32_fp8_e32 v[184:185], v4
	v_cvt_pk_f32_fp8_sdwa v[4:5], v5 src0_sel:WORD_1
	v_pk_fma_f32 v[2:3], v[184:185], v[106:107], v[2:3]
	v_cvt_pk_f32_fp8_e32 v[184:185], v7
	v_pk_fma_f32 v[2:3], v[186:187], v[108:109], v[2:3]
	v_pk_fma_f32 v[2:3], v[188:189], v[110:111], v[2:3]
	v_pk_fma_f32 v[2:3], v[4:5], v[112:113], v[2:3]
	v_cvt_pk_f32_fp8_sdwa v[4:5], v6 src0_sel:WORD_1
	v_add_f32_e32 v186, v2, v3
	v_cvt_pk_f32_fp8_e32 v[2:3], v6
	v_cvt_pk_f32_fp8_sdwa v[6:7], v7 src0_sel:WORD_1
	v_pk_fma_f32 v[2:3], v[2:3], v[98:99], 0 op_sel_hi:[1,1,0]
	v_pk_fma_f32 v[2:3], v[4:5], v[100:101], v[2:3]
	v_cvt_pk_f32_fp8_sdwa v[4:5], v8 src0_sel:WORD_1
	v_pk_fma_f32 v[2:3], v[184:185], v[102:103], v[2:3]
	v_cvt_pk_f32_fp8_e32 v[184:185], v9
	v_pk_fma_f32 v[6:7], v[6:7], v[104:105], v[2:3]
	v_cvt_pk_f32_fp8_e32 v[2:3], v8
	v_cvt_pk_f32_fp8_sdwa v[8:9], v9 src0_sel:WORD_1
	v_pk_fma_f32 v[6:7], v[2:3], v[106:107], v[6:7]
	v_cvt_pk_f32_fp8_e32 v[2:3], v11
	v_pk_fma_f32 v[6:7], v[4:5], v[108:109], v[6:7]
	v_pk_fma_f32 v[6:7], v[184:185], v[110:111], v[6:7]
	v_pk_fma_f32 v[6:7], v[8:9], v[112:113], v[6:7]
	v_cvt_pk_f32_fp8_sdwa v[8:9], v10 src0_sel:WORD_1
	v_add_f32_e32 v4, v6, v7
	v_cvt_pk_f32_fp8_e32 v[6:7], v10
	v_cvt_pk_f32_fp8_sdwa v[10:11], v11 src0_sel:WORD_1
	v_pk_fma_f32 v[6:7], v[6:7], v[98:99], 0 op_sel_hi:[1,1,0]
	v_pk_fma_f32 v[6:7], v[8:9], v[100:101], v[6:7]
	v_cvt_pk_f32_fp8_sdwa v[8:9], v12 src0_sel:WORD_1
	v_pk_fma_f32 v[6:7], v[2:3], v[102:103], v[6:7]
	v_cvt_pk_f32_fp8_e32 v[2:3], v13
	v_pk_fma_f32 v[10:11], v[10:11], v[104:105], v[6:7]
	v_cvt_pk_f32_fp8_e32 v[6:7], v12
	v_cvt_pk_f32_fp8_sdwa v[12:13], v13 src0_sel:WORD_1
	v_pk_fma_f32 v[10:11], v[6:7], v[106:107], v[10:11]
	v_cvt_pk_f32_fp8_e32 v[6:7], v15
	v_pk_fma_f32 v[10:11], v[8:9], v[108:109], v[10:11]
	v_pk_fma_f32 v[10:11], v[2:3], v[110:111], v[10:11]
	v_pk_fma_f32 v[10:11], v[12:13], v[112:113], v[10:11]
	v_cvt_pk_f32_fp8_sdwa v[12:13], v14 src0_sel:WORD_1
	v_add_f32_e32 v8, v10, v11
	v_cvt_pk_f32_fp8_e32 v[10:11], v14
	v_cvt_pk_f32_fp8_sdwa v[14:15], v15 src0_sel:WORD_1
	v_pk_fma_f32 v[10:11], v[10:11], v[98:99], 0 op_sel_hi:[1,1,0]
	v_pk_fma_f32 v[10:11], v[12:13], v[100:101], v[10:11]
	v_cvt_pk_f32_fp8_sdwa v[12:13], v16 src0_sel:WORD_1
	v_pk_fma_f32 v[10:11], v[6:7], v[102:103], v[10:11]
	v_cvt_pk_f32_fp8_e32 v[6:7], v17
	v_pk_fma_f32 v[14:15], v[14:15], v[104:105], v[10:11]
	v_cvt_pk_f32_fp8_e32 v[10:11], v16
	v_cvt_pk_f32_fp8_sdwa v[16:17], v17 src0_sel:WORD_1
	s_waitcnt vmcnt(1)
	v_lshl_or_b32 v172, v30, 7, v1
	v_pk_fma_f32 v[14:15], v[10:11], v[106:107], v[14:15]
	v_cvt_pk_f32_fp8_e32 v[10:11], v23
	v_pk_fma_f32 v[14:15], v[12:13], v[108:109], v[14:15]
	v_lshl_or_b32 v173, v31, 7, v1
	v_pk_fma_f32 v[14:15], v[6:7], v[110:111], v[14:15]
	v_lshl_or_b32 v164, v32, 7, v1
	v_pk_fma_f32 v[14:15], v[16:17], v[112:113], v[14:15]
	v_cvt_pk_f32_fp8_sdwa v[16:17], v22 src0_sel:WORD_1
	v_add_f32_e32 v12, v14, v15
	v_cvt_pk_f32_fp8_e32 v[14:15], v22
	v_cvt_pk_f32_fp8_sdwa v[22:23], v23 src0_sel:WORD_1
	v_lshl_or_b32 v165, v33, 7, v1
	v_lshl_or_b32 v18, v18, 7, v1
	v_pk_fma_f32 v[14:15], v[14:15], v[98:99], 0 op_sel_hi:[1,1,0]
	v_lshl_or_b32 v19, v19, 7, v1
	v_pk_fma_f32 v[14:15], v[16:17], v[100:101], v[14:15]
	v_cvt_pk_f32_fp8_sdwa v[16:17], v24 src0_sel:WORD_1
	v_pk_fma_f32 v[14:15], v[10:11], v[102:103], v[14:15]
	v_cvt_pk_f32_fp8_e32 v[10:11], v25
	v_pk_fma_f32 v[22:23], v[22:23], v[104:105], v[14:15]
	v_cvt_pk_f32_fp8_e32 v[14:15], v24
	v_cvt_pk_f32_fp8_sdwa v[24:25], v25 src0_sel:WORD_1
	global_load_dwordx4 v[180:183], v172, s[10:11]
	global_load_dwordx4 v[176:179], v173, s[10:11]
	v_pk_fma_f32 v[22:23], v[14:15], v[106:107], v[22:23]
	v_cvt_pk_f32_fp8_e32 v[14:15], v27
	v_pk_fma_f32 v[22:23], v[16:17], v[108:109], v[22:23]
	global_load_dwordx4 v[172:175], v164, s[10:11]
	global_load_dwordx4 v[168:171], v165, s[10:11]
	v_pk_fma_f32 v[22:23], v[10:11], v[110:111], v[22:23]
	global_load_dwordx4 v[164:167], v18, s[10:11]
	global_load_dwordx4 v[160:163], v19, s[10:11]
	v_pk_fma_f32 v[22:23], v[24:25], v[112:113], v[22:23]
	v_cvt_pk_f32_fp8_sdwa v[24:25], v26 src0_sel:WORD_1
	v_add_f32_e32 v16, v22, v23
	v_cvt_pk_f32_fp8_e32 v[22:23], v26
	v_cvt_pk_f32_fp8_sdwa v[26:27], v27 src0_sel:WORD_1
	v_lshl_or_b32 v18, v20, 7, v1
	v_lshl_or_b32 v19, v21, 7, v1
	v_pk_fma_f32 v[22:23], v[22:23], v[98:99], 0 op_sel_hi:[1,1,0]
	global_load_dwordx4 v[150:153], v18, s[10:11]
	global_load_dwordx4 v[146:149], v19, s[10:11]
	v_pk_fma_f32 v[22:23], v[24:25], v[100:101], v[22:23]
	v_cvt_pk_f32_fp8_sdwa v[24:25], v28 src0_sel:WORD_1
	v_pk_fma_f32 v[22:23], v[14:15], v[102:103], v[22:23]
	v_cvt_pk_f32_fp8_e32 v[14:15], v29
	v_pk_fma_f32 v[26:27], v[26:27], v[104:105], v[22:23]
	v_cvt_pk_f32_fp8_e32 v[22:23], v28
	v_cvt_pk_f32_fp8_sdwa v[28:29], v29 src0_sel:WORD_1
	v_lshl_or_b32 v18, v62, 7, v1
	v_lshl_or_b32 v19, v63, 7, v1
	v_pk_fma_f32 v[26:27], v[22:23], v[106:107], v[26:27]
	v_cvt_pk_f32_fp8_e32 v[22:23], v35
	v_pk_fma_f32 v[26:27], v[24:25], v[108:109], v[26:27]
	global_load_dwordx4 v[142:145], v18, s[10:11]
; __device__ __forceinline__ f32x2 fp8x2_lo(unsigned w) { return __builtin_amdgcn_cvt_pk_f32_fp8(w, false); }
; __device__ __forceinline__ f32x2 fp8x2_hi(unsigned w) { return __builtin_amdgcn_cvt_pk_f32_fp8(w, true); }
; #define PA_IDS(T) do { const unsigned* kp_ = KP + (size_t)(T) * 256; _Pragma("unroll") for (int qq = 0; qq < 4; ++qq) idv[qq] = *(const u32x4*)(kp_ + 4 * qq); } while (0)
; template <bool NT>
; __device__ __forceinline__ void peer_passA(const Args& a, const PeerWork w) {
;     ...
;     int t = peer_tok(w, q), t1 = peer_tok(w, min(q + qs, ql));
;     PA_IDS(t);
;     PA_GATHER(t, ur, hv);
;     PA_IDS(t1);
; #pragma unroll 1
;     for (;; q += qs) {
;         u32x4 urn[16]; f32x4 hn[4];
;         PA_GATHER(t1, urn, hn);
;         const int t2 = peer_tok(w, min(q + 2 * qs, ql));
;         PA_IDS(t2);
;         float part[16];
; #pragma unroll
;         for (int k = 0; k < 16; ++k) {
;             const unsigned ww[4] = {ur[k].x, ur[k].y, ur[k].z, ur[k].w};
;             f32x2 p2 = {0.f, 0.f};
; #pragma unroll
;             for (int wd = 0; wd < 4; ++wd) { p2 = __builtin_elementwise_fma(fp8x2_lo(ww[wd]), (f32x2){hv[wd][0], hv[wd][1]}, p2); p2 = __builtin_elementwise_fma(fp8x2_hi(ww[wd]), (f32x2){hv[wd][2], hv[wd][3]}, p2); }
;             part[k] = p2[0] + p2[1];
	global_load_dwordx4 v[138:141], v19, s[10:11]
	v_pk_fma_f32 v[26:27], v[14:15], v[110:111], v[26:27]
	v_lshl_or_b32 v18, v64, 7, v1
	v_pk_fma_f32 v[26:27], v[28:29], v[112:113], v[26:27]
	v_cvt_pk_f32_fp8_sdwa v[28:29], v34 src0_sel:WORD_1
	v_add_f32_e32 v24, v26, v27
	v_cvt_pk_f32_fp8_e32 v[26:27], v34
	v_cvt_pk_f32_fp8_sdwa v[34:35], v35 src0_sel:WORD_1
	v_lshl_or_b32 v19, v65, 7, v1
	s_mov_b32 s18, s16
	v_pk_fma_f32 v[26:27], v[26:27], v[98:99], 0 op_sel_hi:[1,1,0]
	s_mov_b32 s16, s14
	v_pk_fma_f32 v[26:27], v[28:29], v[100:101], v[26:27]
	v_cvt_pk_f32_fp8_sdwa v[28:29], v36 src0_sel:WORD_1
	v_pk_fma_f32 v[26:27], v[22:23], v[102:103], v[26:27]
	v_cvt_pk_f32_fp8_e32 v[22:23], v37
	v_pk_fma_f32 v[34:35], v[34:35], v[104:105], v[26:27]
	v_cvt_pk_f32_fp8_e32 v[26:27], v36
	v_cvt_pk_f32_fp8_sdwa v[36:37], v37 src0_sel:WORD_1
	global_load_dwordx4 v[134:137], v18, s[10:11]
	global_load_dwordx4 v[130:133], v19, s[10:11]
	v_pk_fma_f32 v[34:35], v[26:27], v[106:107], v[34:35]
	v_cvt_pk_f32_fp8_e32 v[26:27], v39
	v_pk_fma_f32 v[34:35], v[28:29], v[108:109], v[34:35]
	v_lshl_or_b32 v18, v50, 7, v1
	v_pk_fma_f32 v[34:35], v[22:23], v[110:111], v[34:35]
	v_lshl_or_b32 v19, v51, 7, v1
	v_pk_fma_f32 v[34:35], v[36:37], v[112:113], v[34:35]
	v_cvt_pk_f32_fp8_sdwa v[36:37], v38 src0_sel:WORD_1
	v_add_f32_e32 v28, v34, v35
	v_cvt_pk_f32_fp8_e32 v[34:35], v38
	v_cvt_pk_f32_fp8_sdwa v[38:39], v39 src0_sel:WORD_1
	s_ashr_i32 s17, s14, 31
	v_pk_fma_f32 v[34:35], v[34:35], v[98:99], 0 op_sel_hi:[1,1,0]
	v_pk_fma_f32 v[34:35], v[36:37], v[100:101], v[34:35]
	v_cvt_pk_f32_fp8_sdwa v[36:37], v40 src0_sel:WORD_1
	v_pk_fma_f32 v[34:35], v[26:27], v[102:103], v[34:35]
	v_cvt_pk_f32_fp8_e32 v[26:27], v41
	v_pk_fma_f32 v[38:39], v[38:39], v[104:105], v[34:35]
	v_cvt_pk_f32_fp8_e32 v[34:35], v40
	v_cvt_pk_f32_fp8_sdwa v[40:41], v41 src0_sel:WORD_1
	global_load_dwordx4 v[126:129], v18, s[10:11]
	global_load_dwordx4 v[122:125], v19, s[10:11]
	v_pk_fma_f32 v[38:39], v[34:35], v[106:107], v[38:39]
	v_cvt_pk_f32_fp8_e32 v[34:35], v43
	v_pk_fma_f32 v[38:39], v[36:37], v[108:109], v[38:39]
	v_lshl_or_b32 v18, v52, 7, v1
	v_pk_fma_f32 v[38:39], v[26:27], v[110:111], v[38:39]
	v_lshl_or_b32 v19, v53, 7, v1
	v_pk_fma_f32 v[38:39], v[40:41], v[112:113], v[38:39]
	v_cvt_pk_f32_fp8_sdwa v[40:41], v42 src0_sel:WORD_1
	v_add_f32_e32 v36, v38, v39
	v_cvt_pk_f32_fp8_e32 v[38:39], v42
	v_cvt_pk_f32_fp8_sdwa v[42:43], v43 src0_sel:WORD_1
	s_lshl_b64 s[14:15], s[16:17], 12
	s_add_i32 s17, s12, s13
	v_pk_fma_f32 v[38:39], v[38:39], v[98:99], 0 op_sel_hi:[1,1,0]
	v_pk_fma_f32 v[38:39], v[40:41], v[100:101], v[38:39]
	v_cvt_pk_f32_fp8_sdwa v[40:41], v44 src0_sel:WORD_1
	v_pk_fma_f32 v[38:39], v[34:35], v[102:103], v[38:39]
	v_cvt_pk_f32_fp8_e32 v[34:35], v45
	v_pk_fma_f32 v[42:43], v[42:43], v[104:105], v[38:39]
	v_cvt_pk_f32_fp8_e32 v[38:39], v44
	v_cvt_pk_f32_fp8_sdwa v[44:45], v45 src0_sel:WORD_1
	global_load_dwordx4 v[118:121], v18, s[10:11]
	global_load_dwordx4 v[114:117], v19, s[10:11]
	v_pk_fma_f32 v[42:43], v[38:39], v[106:107], v[42:43]
	v_cvt_pk_f32_fp8_e32 v[38:39], v47
	v_pk_fma_f32 v[42:43], v[40:41], v[108:109], v[42:43]
	v_lshl_add_u64 v[18:19], v[156:157], 0, s[14:15]
	v_pk_fma_f32 v[42:43], v[34:35], v[110:111], v[42:43]
	s_min_i32 s14, s17, 0x3fff
	v_pk_fma_f32 v[42:43], v[44:45], v[112:113], v[42:43]
	v_cvt_pk_f32_fp8_sdwa v[44:45], v46 src0_sel:WORD_1
	v_add_f32_e32 v40, v42, v43
	v_cvt_pk_f32_fp8_e32 v[42:43], v46
	v_cvt_pk_f32_fp8_sdwa v[46:47], v47 src0_sel:WORD_1
	s_ashr_i32 s15, s14, 31
	s_lshl_b64 s[28:29], s[14:15], 10
	v_pk_fma_f32 v[42:43], v[42:43], v[98:99], 0 op_sel_hi:[1,1,0]
	v_lshl_add_u64 v[30:31], v[154:155], 0, s[28:29]
	v_pk_fma_f32 v[42:43], v[44:45], v[100:101], v[42:43]
	v_cvt_pk_f32_fp8_sdwa v[44:45], v48 src0_sel:WORD_1
	v_pk_fma_f32 v[42:43], v[38:39], v[102:103], v[42:43]
	v_cvt_pk_f32_fp8_e32 v[38:39], v49
	v_pk_fma_f32 v[46:47], v[46:47], v[104:105], v[42:43]
	v_cvt_pk_f32_fp8_e32 v[42:43], v48
	v_cvt_pk_f32_fp8_sdwa v[48:49], v49 src0_sel:WORD_1
	global_load_dwordx4 v[82:85], v[18:19], off offset:48
	global_load_dwordx4 v[86:89], v[18:19], off offset:32
	global_load_dwordx4 v[90:93], v[18:19], off offset:16
	global_load_dwordx4 v[94:97], v[18:19], off
	global_load_dwordx4 v[50:53], v[30:31], off offset:48
	global_load_dwordx4 v[62:65], v[30:31], off offset:32
	s_nop 0
	global_load_dwordx4 v[18:21], v[30:31], off offset:16
	s_nop 0
	global_load_dwordx4 v[30:33], v[30:31], off
	v_pk_fma_f32 v[46:47], v[42:43], v[106:107], v[46:47]
	v_cvt_pk_f32_fp8_e32 v[42:43], v55
	v_pk_fma_f32 v[46:47], v[44:45], v[108:109], v[46:47]
	s_ashr_i32 s19, s18, 31
	v_pk_fma_f32 v[46:47], v[38:39], v[110:111], v[46:47]
	s_lshl_b64 s[18:19], s[18:19], 11
	v_pk_fma_f32 v[46:47], v[48:49], v[112:113], v[46:47]
	v_cvt_pk_f32_fp8_sdwa v[48:49], v54 src0_sel:WORD_1
	v_add_f32_e32 v44, v46, v47
	v_cvt_pk_f32_fp8_e32 v[46:47], v54
	v_cvt_pk_f32_fp8_sdwa v[54:55], v55 src0_sel:WORD_1
	s_add_i32 s12, s22, s12
	s_cmpk_gt_i32 s12, 0x3fff
	v_pk_fma_f32 v[46:47], v[46:47], v[98:99], 0 op_sel_hi:[1,1,0]
	v_readfirstlane_b32 s12, v0
	v_pk_fma_f32 v[46:47], v[48:49], v[100:101], v[46:47]
	v_cvt_pk_f32_fp8_sdwa v[48:49], v56 src0_sel:WORD_1
	v_pk_fma_f32 v[46:47], v[42:43], v[102:103], v[46:47]
	v_cvt_pk_f32_fp8_e32 v[42:43], v57
	v_pk_fma_f32 v[54:55], v[54:55], v[104:105], v[46:47]
	v_cvt_pk_f32_fp8_e32 v[46:47], v56
	v_cvt_pk_f32_fp8_sdwa v[56:57], v57 src0_sel:WORD_1
	v_pk_fma_f32 v[54:55], v[46:47], v[106:107], v[54:55]
	s_nop 0
	v_pk_fma_f32 v[54:55], v[48:49], v[108:109], v[54:55]
	v_cvt_pk_f32_fp8_e32 v[46:47], v59
	v_pk_fma_f32 v[54:55], v[42:43], v[110:111], v[54:55]
; __device__ __forceinline__ f32x2 fp8x2_lo(unsigned w) { return __builtin_amdgcn_cvt_pk_f32_fp8(w, false); }
; __device__ __forceinline__ f32x2 fp8x2_hi(unsigned w) { return __builtin_amdgcn_cvt_pk_f32_fp8(w, true); }
; template <bool NT>
; __device__ __forceinline__ void peer_passA(const Args& a, const PeerWork w) {
;     ...
; #pragma unroll
;         for (int k = 0; k < 16; ++k) {
;             const unsigned ww[4] = {ur[k].x, ur[k].y, ur[k].z, ur[k].w};
;             f32x2 p2 = {0.f, 0.f};
; #pragma unroll
;             for (int wd = 0; wd < 4; ++wd) { p2 = __builtin_elementwise_fma(fp8x2_lo(ww[wd]), (f32x2){hv[wd][0], hv[wd][1]}, p2); p2 = __builtin_elementwise_fma(fp8x2_hi(ww[wd]), (f32x2){hv[wd][2], hv[wd][3]}, p2); }
;             part[k] = p2[0] + p2[1];
;         }
	s_nop 0
	v_pk_fma_f32 v[54:55], v[56:57], v[112:113], v[54:55]
	v_cvt_pk_f32_fp8_sdwa v[56:57], v58 src0_sel:WORD_1
	v_add_f32_e32 v48, v54, v55
	v_cvt_pk_f32_fp8_e32 v[54:55], v58
	v_cvt_pk_f32_fp8_sdwa v[58:59], v59 src0_sel:WORD_1
	v_pk_fma_f32 v[54:55], v[54:55], v[98:99], 0 op_sel_hi:[1,1,0]
	s_nop 0
	v_pk_fma_f32 v[54:55], v[56:57], v[100:101], v[54:55]
	v_cvt_pk_f32_fp8_sdwa v[56:57], v60 src0_sel:WORD_1
	v_pk_fma_f32 v[54:55], v[46:47], v[102:103], v[54:55]
	v_cvt_pk_f32_fp8_e32 v[46:47], v61
	v_pk_fma_f32 v[58:59], v[58:59], v[104:105], v[54:55]
	v_cvt_pk_f32_fp8_e32 v[54:55], v60
	v_cvt_pk_f32_fp8_sdwa v[60:61], v61 src0_sel:WORD_1
	v_pk_fma_f32 v[58:59], v[54:55], v[106:107], v[58:59]
	s_nop 0
	v_pk_fma_f32 v[58:59], v[56:57], v[108:109], v[58:59]
	v_cvt_pk_f32_fp8_e32 v[54:55], v67
	v_pk_fma_f32 v[58:59], v[46:47], v[110:111], v[58:59]
	s_nop 0
	v_pk_fma_f32 v[58:59], v[60:61], v[112:113], v[58:59]
	v_cvt_pk_f32_fp8_sdwa v[60:61], v66 src0_sel:WORD_1
	v_add_f32_e32 v56, v58, v59
	v_cvt_pk_f32_fp8_e32 v[58:59], v66
	v_cvt_pk_f32_fp8_sdwa v[66:67], v67 src0_sel:WORD_1
	v_pk_fma_f32 v[58:59], v[58:59], v[98:99], 0 op_sel_hi:[1,1,0]
	s_nop 0
	v_pk_fma_f32 v[58:59], v[60:61], v[100:101], v[58:59]
	v_cvt_pk_f32_fp8_sdwa v[60:61], v68 src0_sel:WORD_1
	v_pk_fma_f32 v[58:59], v[54:55], v[102:103], v[58:59]
	v_cvt_pk_f32_fp8_e32 v[54:55], v69
	v_pk_fma_f32 v[66:67], v[66:67], v[104:105], v[58:59]
	v_cvt_pk_f32_fp8_e32 v[58:59], v68
	v_cvt_pk_f32_fp8_sdwa v[68:69], v69 src0_sel:WORD_1
	v_pk_fma_f32 v[66:67], v[58:59], v[106:107], v[66:67]
	s_nop 0
	v_pk_fma_f32 v[66:67], v[60:61], v[108:109], v[66:67]
	v_cvt_pk_f32_fp8_e32 v[58:59], v71
	v_pk_fma_f32 v[66:67], v[54:55], v[110:111], v[66:67]
	s_nop 0
	v_pk_fma_f32 v[66:67], v[68:69], v[112:113], v[66:67]
	v_cvt_pk_f32_fp8_sdwa v[68:69], v70 src0_sel:WORD_1
	v_add_f32_e32 v60, v66, v67
	v_cvt_pk_f32_fp8_e32 v[66:67], v70
	v_cvt_pk_f32_fp8_sdwa v[70:71], v71 src0_sel:WORD_1
	v_pk_fma_f32 v[66:67], v[66:67], v[98:99], 0 op_sel_hi:[1,1,0]
	s_nop 0
	v_pk_fma_f32 v[66:67], v[68:69], v[100:101], v[66:67]
	v_cvt_pk_f32_fp8_sdwa v[68:69], v72 src0_sel:WORD_1
	v_pk_fma_f32 v[66:67], v[58:59], v[102:103], v[66:67]
	v_cvt_pk_f32_fp8_e32 v[58:59], v73
	v_pk_fma_f32 v[70:71], v[70:71], v[104:105], v[66:67]
	v_cvt_pk_f32_fp8_e32 v[66:67], v72
	v_cvt_pk_f32_fp8_sdwa v[72:73], v73 src0_sel:WORD_1
	v_pk_fma_f32 v[70:71], v[66:67], v[106:107], v[70:71]
	s_nop 0
	v_pk_fma_f32 v[70:71], v[68:69], v[108:109], v[70:71]
	v_cvt_pk_f32_fp8_e32 v[66:67], v75
	v_pk_fma_f32 v[70:71], v[58:59], v[110:111], v[70:71]
	s_nop 0
	v_pk_fma_f32 v[70:71], v[72:73], v[112:113], v[70:71]
	v_cvt_pk_f32_fp8_sdwa v[72:73], v74 src0_sel:WORD_1
	v_add_f32_e32 v68, v70, v71
	v_cvt_pk_f32_fp8_e32 v[70:71], v74
	v_cvt_pk_f32_fp8_sdwa v[74:75], v75 src0_sel:WORD_1
	v_pk_fma_f32 v[70:71], v[70:71], v[98:99], 0 op_sel_hi:[1,1,0]
	s_nop 0
	v_pk_fma_f32 v[70:71], v[72:73], v[100:101], v[70:71]
	v_cvt_pk_f32_fp8_sdwa v[72:73], v76 src0_sel:WORD_1
	v_pk_fma_f32 v[70:71], v[66:67], v[102:103], v[70:71]
	v_cvt_pk_f32_fp8_e32 v[66:67], v77
	v_pk_fma_f32 v[74:75], v[74:75], v[104:105], v[70:71]
	v_cvt_pk_f32_fp8_e32 v[70:71], v76
	v_cvt_pk_f32_fp8_sdwa v[76:77], v77 src0_sel:WORD_1
	v_pk_fma_f32 v[74:75], v[70:71], v[106:107], v[74:75]
	s_nop 0
	v_pk_fma_f32 v[74:75], v[72:73], v[108:109], v[74:75]
	v_cvt_pk_f32_fp8_e32 v[70:71], v79
	v_pk_fma_f32 v[74:75], v[66:67], v[110:111], v[74:75]
	s_nop 0
	v_pk_fma_f32 v[74:75], v[76:77], v[112:113], v[74:75]
	v_cvt_pk_f32_fp8_sdwa v[76:77], v78 src0_sel:WORD_1
	v_add_f32_e32 v72, v74, v75
	v_cvt_pk_f32_fp8_e32 v[74:75], v78
	v_cvt_pk_f32_fp8_sdwa v[78:79], v79 src0_sel:WORD_1
	v_pk_fma_f32 v[98:99], v[74:75], v[98:99], 0 op_sel_hi:[1,1,0]
	s_nop 0
	v_pk_fma_f32 v[98:99], v[76:77], v[100:101], v[98:99]
	v_cvt_pk_f32_fp8_e32 v[100:101], v81
	v_pk_fma_f32 v[102:103], v[70:71], v[102:103], v[98:99]
	v_cvt_pk_f32_fp8_sdwa v[98:99], v80 src0_sel:WORD_1
	v_pk_fma_f32 v[102:103], v[78:79], v[104:105], v[102:103]
; __device__ __forceinline__ unsigned cvt_pk_bf16(float lo, float hi) { unsigned r; asm volatile("v_cvt_pk_bf16_f32 %0, %1, %2" : "=v"(r) : "v"(lo), "v"(hi)); return r; }
; template <int CTRL> __device__ __forceinline__ float dpp_f(float x) { return __uint_as_float((unsigned)__builtin_amdgcn_update_dpp(0, (int)__float_as_uint(x), CTRL, 0xf, 0xf, false)); }
; __device__ __forceinline__ float xor4_f(float x) { float r = dpp_bank_f<0x104, 0x5>(0.f, x); return dpp_bank_f<0x114, 0xa>(r, x); }
; template <bool NT>
; __device__ __forceinline__ void peer_passA(const Args& a, const PeerWork w) {
;     ...
;         float w8[8], w4[4], w2[2];
;         { const bool up = (lane & 4) != 0;
; #pragma unroll
;           for (int m = 0; m < 8; ++m) { const float keep = up ? part[m + 8] : part[m], send = up ? part[m] : part[m + 8]; w8[m] = keep + xor4_f(send); } }
;         { const bool up = (lane & 2) != 0;
; #pragma unroll
;           for (int m = 0; m < 4; ++m) { const float keep = up ? w8[m + 4] : w8[m], send = up ? w8[m] : w8[m + 4]; w4[m] = keep + dpp_f<0x4E>(send); } }
;         { const bool up = (lane & 1) != 0;
; #pragma unroll
;           for (int m = 0; m < 2; ++m) { const float keep = up ? w4[m + 2] : w4[m], send = up ? w4[m] : w4[m + 2]; w2[m] = keep + dpp_f<0xB1>(send); } }
;         PD[(size_t)t * 512] = cvt_pk_bf16(w2[0], w2[1]);
;         if (q + qs > ql) break;
; #pragma unroll
;         for (int k = 0; k < 16; ++k) ur[k] = urn[k];
; #pragma unroll
;         for (int qq = 0; qq < 4; ++qq) hv[qq] = hn[qq];
;         t = t1; t1 = t2;
;     }
	v_cvt_pk_f32_fp8_e32 v[104:105], v80
	v_cvt_pk_f32_fp8_sdwa v[78:79], v81 src0_sel:WORD_1
	v_pk_fma_f32 v[106:107], v[104:105], v[106:107], v[102:103]
	s_nop 0
	v_pk_fma_f32 v[106:107], v[98:99], v[108:109], v[106:107]
	v_mov_b32_e32 v108, 0
	v_pk_fma_f32 v[110:111], v[100:101], v[110:111], v[106:107]
	v_mov_b32_e32 v106, 0
	v_pk_fma_f32 v[110:111], v[78:79], v[112:113], v[110:111]
	v_cndmask_b32_e64 v112, v186, v40, s[0:1]
	v_mov_b32_e32 v113, 0
	v_add_f32_e32 v110, v110, v111
	v_cndmask_b32_e64 v111, v40, v186, s[0:1]
	v_mov_b32_dpp v113, v112 row_shl:4 row_mask:0xf bank_mask:0x5
	v_mov_b32_e32 v107, 0
	v_mov_b32_e32 v109, 0
	v_mov_b32_dpp v113, v112 row_shr:4 row_mask:0xf bank_mask:0xa
	v_add_f32_e32 v111, v111, v113
	v_cndmask_b32_e64 v113, v4, v44, s[0:1]
	v_cndmask_b32_e64 v112, v44, v4, s[0:1]
	v_mov_b32_e32 v102, 0
	v_mov_b32_dpp v106, v113 row_shl:4 row_mask:0xf bank_mask:0x5
	v_mov_b32_e32 v103, 0
	s_nop 0
	v_mov_b32_dpp v106, v113 row_shr:4 row_mask:0xf bank_mask:0xa
	v_add_f32_e32 v112, v112, v106
	v_cndmask_b32_e64 v106, v8, v48, s[0:1]
	v_cndmask_b32_e64 v113, v48, v8, s[0:1]
	s_nop 0
	v_mov_b32_dpp v107, v106 row_shl:4 row_mask:0xf bank_mask:0x5
	s_nop 1
	v_mov_b32_dpp v107, v106 row_shr:4 row_mask:0xf bank_mask:0xa
	v_add_f32_e32 v113, v113, v107
	v_cndmask_b32_e64 v107, v12, v56, s[0:1]
	v_cndmask_b32_e64 v106, v56, v12, s[0:1]
	s_nop 0
	v_mov_b32_dpp v108, v107 row_shl:4 row_mask:0xf bank_mask:0x5
	s_nop 1
	v_mov_b32_dpp v108, v107 row_shr:4 row_mask:0xf bank_mask:0xa
	v_add_f32_e32 v106, v106, v108
	v_cndmask_b32_e64 v108, v16, v60, s[0:1]
	v_cndmask_b32_e64 v107, v60, v16, s[0:1]
	s_nop 0
	v_mov_b32_dpp v109, v108 row_shl:4 row_mask:0xf bank_mask:0x5
	s_nop 1
	v_mov_b32_dpp v109, v108 row_shr:4 row_mask:0xf bank_mask:0xa
	v_add_f32_e32 v107, v107, v109
	v_cndmask_b32_e64 v109, v24, v68, s[0:1]
	v_cndmask_b32_e64 v108, v68, v24, s[0:1]
	s_nop 0
	v_mov_b32_dpp v102, v109 row_shl:4 row_mask:0xf bank_mask:0x5
	s_nop 1
	v_mov_b32_dpp v102, v109 row_shr:4 row_mask:0xf bank_mask:0xa
	v_add_f32_e32 v108, v108, v102
	v_cndmask_b32_e64 v102, v28, v72, s[0:1]
	v_cndmask_b32_e64 v109, v72, v28, s[0:1]
	s_nop 0
	v_mov_b32_dpp v103, v102 row_shl:4 row_mask:0xf bank_mask:0x5
	s_nop 1
	v_mov_b32_dpp v103, v102 row_shr:4 row_mask:0xf bank_mask:0xa
	v_add_f32_e32 v109, v109, v103
	v_cndmask_b32_e64 v102, v110, v36, s[0:1]
	v_cndmask_b32_e64 v110, v36, v110, s[0:1]
	v_mov_b32_e32 v103, 0
	s_nop 1
	v_mov_b32_dpp v103, v110 row_shl:4 row_mask:0xf bank_mask:0x5
	s_nop 1
	v_mov_b32_dpp v103, v110 row_shr:4 row_mask:0xf bank_mask:0xa
	v_add_f32_e32 v110, v102, v103
	v_cndmask_b32_e64 v102, v107, v111, s[4:5]
	v_cndmask_b32_e64 v111, v111, v107, s[4:5]
	v_cndmask_b32_e64 v107, v108, v112, s[4:5]
	v_cndmask_b32_e64 v112, v112, v108, s[4:5]
	v_add_f32_dpp v111, v111, v102 quad_perm:[2,3,0,1] row_mask:0xf bank_mask:0xf bound_ctrl:1
	s_nop 0
	v_add_f32_dpp v112, v112, v107 quad_perm:[2,3,0,1] row_mask:0xf bank_mask:0xf bound_ctrl:1
	v_cndmask_b32_e64 v107, v109, v113, s[4:5]
	v_cndmask_b32_e64 v113, v113, v109, s[4:5]
	s_nop 1
	v_add_f32_dpp v113, v113, v107 quad_perm:[2,3,0,1] row_mask:0xf bank_mask:0xf bound_ctrl:1
	v_cndmask_b32_e64 v107, v110, v106, s[4:5]
	v_cndmask_b32_e64 v110, v106, v110, s[4:5]
	v_cndmask_b32_e64 v106, v113, v111, s[6:7]
	v_cndmask_b32_e64 v111, v111, v113, s[6:7]
	v_add_f32_dpp v110, v110, v107 quad_perm:[2,3,0,1] row_mask:0xf bank_mask:0xf bound_ctrl:1
	v_cndmask_b32_e64 v113, v110, v112, s[6:7]
	v_cndmask_b32_e64 v110, v112, v110, s[6:7]
	v_add_f32_dpp v111, v111, v106 quad_perm:[1,0,3,2] row_mask:0xf bank_mask:0xf bound_ctrl:1
	s_nop 0
	v_add_f32_dpp v110, v110, v113 quad_perm:[1,0,3,2] row_mask:0xf bank_mask:0xf bound_ctrl:1
	v_cvt_pk_bf16_f32 v112, v111, v110
	v_lshl_add_u64 v[110:111], v[158:159], 0, s[18:19]
	s_mov_b64 s[18:19], -1
	global_store_dword v[110:111], v112, off
	s_cbranch_scc1 .Lpa_x2_a6
	s_sub_i32 s12, s17, s22
	s_mov_b64 s[18:19], 0
	s_branch .LBB0_1321
.Lpa_x2_a6:
	s_waitcnt vmcnt(0)
	s_branch .LBB0_1323

; __device__ __forceinline__ f32x2 fp8x2_lo(unsigned w) { return __builtin_amdgcn_cvt_pk_f32_fp8(w, false); }
; __device__ __forceinline__ f32x2 fp8x2_hi(unsigned w) { return __builtin_amdgcn_cvt_pk_f32_fp8(w, true); }
; #define PB_IDS(T) do { const unsigned* kp_ = KP + (size_t)(T) * 256; _Pragma("unroll") for (int qq = 0; qq < 4; ++qq) idv[qq] = *(const u32x4*)(kp_ + 4 * qq); } while (0)
; template <bool NT>
; __device__ __forceinline__ void peer_passB(const Args& a, const PeerWork w) {
;     ...
;     const unsigned char* Vs = ws + WS_V8 + (size_t)j * SLICE_BYTES; const unsigned sub16 = 16u * (unsigned)sub;
;     const unsigned* KP = (const unsigned*)(ws + WS_PEERK) + 16 * r;
;     const float* CO = (const float*)(ws + WS_COEF) + 16 * r;
;     const float* H = (const float*)(ws + WS_H) + 128 * j + 16 * sub + 2 * r;
;     float* Y = a.out + 128 * j + 16 * sub + 2 * r;
;     const int qs = w.qstep, ql = w.nq - 1;
;     int q = w.q0;
;     if (q > ql) return;
;     u32x4 idv[4], vr[16]; f32x4 cf[4]; f32x2 hv;
;     ...
;     int t = peer_tok(w, q), t1 = peer_tok(w, min(q + qs, ql));
;     PB_IDS(t);
;     PB_GATHER(t, vr, cf, hv);
;     PB_IDS(t1);
;     ...
;         for (int k = 0; k < 16; ++k) {
;             const unsigned ww[4] = {vr[k].x, vr[k].y, vr[k].z, vr[k].w};
;             const float c = cf[k >> 2][k & 3]; const f32x2 c2 = {c, c};
; #pragma unroll
;             for (int wd = 0; wd < 4; ++wd) { acc[2 * wd] = __builtin_elementwise_fma(fp8x2_lo(ww[wd]), c2, acc[2 * wd]); acc[2 * wd + 1] = __builtin_elementwise_fma(fp8x2_hi(ww[wd]), c2, acc[2 * wd + 1]); }
.LBB0_1584:
	s_cmp_lt_i32 s26, 9
	s_cselect_b64 s[8:9], -1, 0
	s_and_b64 s[0:1], s[8:9], s[0:1]
	s_andn2_b64 vcc, exec, s[0:1]
	s_mul_i32 s2, s43, s42
	s_cbranch_vccnz .LBB0_1593
	s_and_b32 s16, s86, 7
	s_ashr_i32 s0, s86, 3
	s_add_i32 s10, s2, s0
	s_and_b32 s22, s3, -8
	s_lshl_b32 s17, s16, 21
	s_add_u32 s0, s24, 0x1b346000
	v_lshlrev_b32_e32 v1, 4, v0
	s_addc_u32 s1, s25, 0
	s_lshl_b32 s4, s16, 9
	v_and_b32_e32 v1, 0x70, v1
	s_add_u32 s4, s24, s4
	s_addc_u32 s5, s25, 0
	s_waitcnt vmcnt(0)
	v_mov_b32_e32 v71, 0
	v_lshlrev_b32_e32 v70, 2, v1
	v_lshl_add_u64 v[2:3], s[4:5], 0, v[70:71]
	s_mov_b64 s[4:5], 0xbb46000
	s_cmpk_gt_i32 s10, 0x3fff
	v_lshl_add_u64 v[178:179], v[2:3], 0, s[4:5]
	s_cbranch_scc1 .LBB0_1588
	s_lshl_b32 s6, s16, 7
	s_add_u32 s4, s24, s17
	s_addc_u32 s5, s25, 0
	s_add_u32 s4, s4, 0x3ca6000
	s_addc_u32 s5, s5, 0
	s_lshl_b32 s6, s6, 2
	v_bfe_u32 v6, v0, 3, 3
	s_add_u32 s12, s94, s6
	v_lshlrev_b32_e32 v2, 6, v6
	v_mov_b32_e32 v3, v71
	s_addc_u32 s13, s95, 0
	s_ashr_i32 s11, s10, 31
	v_lshl_add_u64 v[180:181], s[0:1], 0, v[2:3]
	s_lshl_b64 s[6:7], s[10:11], 10
	v_lshl_add_u64 v[4:5], v[180:181], 0, s[6:7]
	global_load_dwordx4 v[14:17], v[4:5], off
	global_load_dwordx4 v[18:21], v[4:5], off offset:16
	global_load_dwordx4 v[26:29], v[4:5], off offset:32
	global_load_dwordx4 v[30:33], v[4:5], off offset:48
	s_mov_b64 s[6:7], 0x20846000
	v_lshl_add_u64 v[2:3], s[24:25], 0, v[2:3]
	v_lshl_add_u64 v[184:185], v[2:3], 0, s[6:7]
	s_add_i32 s6, s10, s22
	s_min_i32 s6, s6, 0x3fff
	s_lshl_b64 s[14:15], s[10:11], 9
	s_ashr_i32 s7, s6, 31
	v_mov_b32_e32 v73, v71
	v_lshlrev_b32_e32 v72, 3, v6
	v_lshl_add_u64 v[2:3], v[184:185], 0, s[14:15]
	s_lshl_b64 s[14:15], s[6:7], 10
	v_lshl_add_u64 v[182:183], v[178:179], 0, v[72:73]
	s_lshl_b64 s[18:19], s[10:11], 12
	v_lshl_add_u64 v[76:77], v[180:181], 0, s[14:15]
	v_lshl_add_u64 v[74:75], v[182:183], 0, s[18:19]
	global_load_dwordx4 v[22:25], v[2:3], off offset:48
	global_load_dwordx4 v[38:41], v[2:3], off offset:32
	global_load_dwordx4 v[62:65], v[2:3], off offset:16
	global_load_dwordx4 v[162:165], v[2:3], off
	s_nop 0
	global_load_dwordx4 v[2:5], v[76:77], off offset:48
	global_load_dwordx4 v[6:9], v[76:77], off offset:32
	global_load_dwordx4 v[10:13], v[76:77], off offset:16
	v_lshl_add_u64 v[70:71], s[12:13], 0, v[70:71]
	v_lshl_add_u64 v[186:187], v[70:71], 0, v[72:73]
	v_and_b32_e32 v70, 8, v0
	s_lshl_b32 s11, s22, 1
	v_cmp_eq_u32_e32 vcc, 0, v70
	s_mov_b32 s12, s10
	s_mov_b32 s18, s10
	s_waitcnt vmcnt(10)
	v_lshl_or_b32 v14, v14, 7, v1
	v_lshl_or_b32 v15, v15, 7, v1
	v_lshl_or_b32 v16, v16, 7, v1
	v_lshl_or_b32 v17, v17, 7, v1
	s_waitcnt vmcnt(9)
	v_lshl_or_b32 v18, v18, 7, v1
	v_lshl_or_b32 v19, v19, 7, v1
	v_lshl_or_b32 v20, v20, 7, v1
	v_lshl_or_b32 v21, v21, 7, v1
	s_waitcnt vmcnt(8)
	v_lshl_or_b32 v78, v26, 7, v1
	v_lshl_or_b32 v79, v27, 7, v1
	v_lshl_or_b32 v80, v28, 7, v1
	v_lshl_or_b32 v81, v29, 7, v1
	s_waitcnt vmcnt(7)
	v_lshl_or_b32 v82, v30, 7, v1
	v_lshl_or_b32 v83, v31, 7, v1
	v_lshl_or_b32 v84, v32, 7, v1
	v_lshl_or_b32 v85, v33, 7, v1
	global_load_dwordx4 v[174:177], v14, s[4:5]
	global_load_dwordx4 v[170:173], v15, s[4:5]
	global_load_dwordx4 v[166:169], v16, s[4:5]
	global_load_dwordx4 v[158:161], v17, s[4:5]
	global_load_dwordx4 v[138:141], v18, s[4:5]
	global_load_dwordx4 v[94:97], v19, s[4:5]
	global_load_dwordx4 v[66:69], v20, s[4:5]
	global_load_dwordx4 v[58:61], v21, s[4:5]
	global_load_dwordx4 v[54:57], v78, s[4:5]
	global_load_dwordx4 v[50:53], v79, s[4:5]
	global_load_dwordx4 v[46:49], v80, s[4:5]
	global_load_dwordx4 v[42:45], v81, s[4:5]
	global_load_dwordx4 v[34:37], v82, s[4:5]
	global_load_dwordx4 v[30:33], v83, s[4:5]
	global_load_dwordx4 v[26:29], v84, s[4:5]
	global_load_dwordx4 v[18:21], v85, s[4:5]
	global_load_dwordx2 v[190:191], v[74:75], off
	global_load_dwordx4 v[14:17], v[76:77], off
	s_waitcnt vmcnt(0)
.LBB0_1587:
	s_waitcnt vmcnt(23)
	v_cvt_pk_f32_fp8_e32 v[192:193], v174
	s_waitcnt vmcnt(19)
	v_cvt_pk_f32_fp8_e32 v[204:205], v170
	v_cvt_pk_f32_fp8_sdwa v[194:195], v174 src0_sel:WORD_1
	v_cvt_pk_f32_fp8_e32 v[196:197], v175
	s_waitcnt vmcnt(6)
	v_pk_fma_f32 v[192:193], v[192:193], v[162:163], 0 op_sel_hi:[1,0,0]
	v_cvt_pk_f32_fp8_sdwa v[174:175], v175 src0_sel:WORD_1
	v_pk_fma_f32 v[192:193], v[204:205], v[162:163], v[192:193] op_sel:[0,1,0]
	v_cvt_pk_f32_fp8_sdwa v[204:205], v170 src0_sel:WORD_1
	v_pk_fma_f32 v[194:195], v[194:195], v[162:163], 0 op_sel_hi:[1,0,0]
	v_pk_fma_f32 v[174:175], v[174:175], v[162:163], 0 op_sel_hi:[1,0,0]
	v_cvt_pk_f32_fp8_e32 v[198:199], v176
	v_pk_fma_f32 v[194:195], v[204:205], v[162:163], v[194:195] op_sel:[0,1,0]
	v_cvt_pk_f32_fp8_e32 v[204:205], v171
	v_cvt_pk_f32_fp8_sdwa v[170:171], v171 src0_sel:WORD_1
	v_pk_fma_f32 v[198:199], v[198:199], v[162:163], 0 op_sel_hi:[1,0,0]
	v_cvt_pk_f32_fp8_sdwa v[200:201], v176 src0_sel:WORD_1
	v_cvt_pk_f32_fp8_e32 v[202:203], v177
	v_pk_fma_f32 v[170:171], v[170:171], v[162:163], v[174:175] op_sel:[0,1,0]
	v_cvt_pk_f32_fp8_e32 v[174:175], v172
	v_pk_fma_f32 v[200:201], v[200:201], v[162:163], 0 op_sel_hi:[1,0,0]
	v_cvt_pk_f32_fp8_sdwa v[176:177], v177 src0_sel:WORD_1
	v_pk_fma_f32 v[196:197], v[196:197], v[162:163], 0 op_sel_hi:[1,0,0]
	v_pk_fma_f32 v[174:175], v[174:175], v[162:163], v[198:199] op_sel:[0,1,0]
	v_cvt_pk_f32_fp8_sdwa v[198:199], v172 src0_sel:WORD_1
	v_pk_fma_f32 v[202:203], v[202:203], v[162:163], 0 op_sel_hi:[1,0,0]
	v_pk_fma_f32 v[176:177], v[176:177], v[162:163], 0 op_sel_hi:[1,0,0]
	v_pk_fma_f32 v[196:197], v[204:205], v[162:163], v[196:197] op_sel:[0,1,0]
	v_pk_fma_f32 v[198:199], v[198:199], v[162:163], v[200:201] op_sel:[0,1,0]
	v_cvt_pk_f32_fp8_e32 v[200:201], v173
	v_cvt_pk_f32_fp8_sdwa v[172:173], v173 src0_sel:WORD_1
	s_waitcnt vmcnt(3)
; __device__ __forceinline__ f32x2 fp8x2_lo(unsigned w) { return __builtin_amdgcn_cvt_pk_f32_fp8(w, false); }
; __device__ __forceinline__ f32x2 fp8x2_hi(unsigned w) { return __builtin_amdgcn_cvt_pk_f32_fp8(w, true); }
; #define PB_IDS(T) do { const unsigned* kp_ = KP + (size_t)(T) * 256; _Pragma("unroll") for (int qq = 0; qq < 4; ++qq) idv[qq] = *(const u32x4*)(kp_ + 4 * qq); } while (0)
; template <bool NT>
; __device__ __forceinline__ void peer_passB(const Args& a, const PeerWork w) {
;     ...
;     int t = peer_tok(w, q), t1 = peer_tok(w, min(q + qs, ql));
;     PB_IDS(t);
;     PB_GATHER(t, vr, cf, hv);
;     PB_IDS(t1);
; #pragma unroll 1
;     for (;; q += qs) {
;         u32x4 vrn[16]; f32x4 cfn[4]; f32x2 hn;
;         PB_GATHER(t1, vrn, cfn, hn);
;         const int t2 = peer_tok(w, min(q + 2 * qs, ql));
;         PB_IDS(t2);
;         f32x2 acc[8];
; #pragma unroll
;         for (int m = 0; m < 8; ++m) acc[m] = (f32x2){0.f, 0.f};
; #pragma unroll
;         for (int k = 0; k < 16; ++k) {
;             const unsigned ww[4] = {vr[k].x, vr[k].y, vr[k].z, vr[k].w};
;             const float c = cf[k >> 2][k & 3]; const f32x2 c2 = {c, c};
; #pragma unroll
;             for (int wd = 0; wd < 4; ++wd) { acc[2 * wd] = __builtin_elementwise_fma(fp8x2_lo(ww[wd]), c2, acc[2 * wd]); acc[2 * wd + 1] = __builtin_elementwise_fma(fp8x2_hi(ww[wd]), c2, acc[2 * wd + 1]); }
	v_lshl_or_b32 v6, v6, 7, v1
	v_lshl_or_b32 v2, v2, 7, v1
	v_pk_fma_f32 v[200:201], v[200:201], v[162:163], v[202:203] op_sel:[0,1,0]
	v_pk_fma_f32 v[162:163], v[172:173], v[162:163], v[176:177] op_sel:[0,1,0]
	v_cvt_pk_f32_fp8_e32 v[172:173], v166
	v_cvt_pk_f32_fp8_sdwa v[176:177], v166 src0_sel:WORD_1
	s_waitcnt vmcnt(1)
	v_lshl_or_b32 v14, v14, 7, v1
	v_lshl_or_b32 v10, v10, 7, v1
	v_pk_fma_f32 v[172:173], v[172:173], v[164:165], v[192:193] op_sel_hi:[1,0,1]
	v_cvt_pk_f32_fp8_e32 v[192:193], v167
	v_cvt_pk_f32_fp8_sdwa v[166:167], v167 src0_sel:WORD_1
	v_pk_fma_f32 v[176:177], v[176:177], v[164:165], v[194:195] op_sel_hi:[1,0,1]
	v_cvt_pk_f32_fp8_e32 v[194:195], v169
	v_pk_fma_f32 v[192:193], v[192:193], v[164:165], v[196:197] op_sel_hi:[1,0,1]
	v_pk_fma_f32 v[166:167], v[166:167], v[164:165], v[170:171] op_sel_hi:[1,0,1]
	v_cvt_pk_f32_fp8_e32 v[170:171], v168
	v_pk_fma_f32 v[194:195], v[194:195], v[164:165], v[200:201] op_sel_hi:[1,0,1]
	global_load_dwordx4 v[106:109], v6, s[4:5]
	global_load_dwordx4 v[122:125], v2, s[4:5]
	v_pk_fma_f32 v[170:171], v[170:171], v[164:165], v[174:175] op_sel_hi:[1,0,1]
	v_cvt_pk_f32_fp8_sdwa v[174:175], v168 src0_sel:WORD_1
	v_cvt_pk_f32_fp8_sdwa v[168:169], v169 src0_sel:WORD_1
	v_lshl_or_b32 v6, v7, 7, v1
	v_lshl_or_b32 v2, v3, 7, v1
	v_pk_fma_f32 v[174:175], v[174:175], v[164:165], v[198:199] op_sel_hi:[1,0,1]
	v_pk_fma_f32 v[162:163], v[168:169], v[164:165], v[162:163] op_sel_hi:[1,0,1]
	v_cvt_pk_f32_fp8_e32 v[168:169], v158
	v_mov_b32_e32 v164, v165
	s_mov_b32 s14, s6
	global_load_dwordx4 v[70:73], v14, s[4:5]
	global_load_dwordx4 v[86:89], v10, s[4:5]
	v_pk_fma_f32 v[168:169], v[168:169], v[164:165], v[172:173] op_sel_hi:[1,0,1]
	v_cvt_pk_f32_fp8_sdwa v[172:173], v158 src0_sel:WORD_1
	v_lshl_or_b32 v14, v15, 7, v1
	v_lshl_or_b32 v10, v11, 7, v1
	global_load_dwordx4 v[110:113], v6, s[4:5]
	global_load_dwordx4 v[126:129], v2, s[4:5]
	v_pk_fma_f32 v[172:173], v[172:173], v[164:165], v[176:177] op_sel_hi:[1,0,1]
	v_cvt_pk_f32_fp8_e32 v[176:177], v159
	v_cvt_pk_f32_fp8_sdwa v[158:159], v159 src0_sel:WORD_1
	v_lshl_or_b32 v6, v8, 7, v1
	v_lshl_or_b32 v2, v4, 7, v1
	v_pk_fma_f32 v[176:177], v[176:177], v[164:165], v[192:193] op_sel_hi:[1,0,1]
	v_pk_fma_f32 v[158:159], v[158:159], v[164:165], v[166:167] op_sel_hi:[1,0,1]
	v_cvt_pk_f32_fp8_e32 v[166:167], v160
	s_ashr_i32 s15, s6, 31
	global_load_dwordx4 v[74:77], v14, s[4:5]
	global_load_dwordx4 v[90:93], v10, s[4:5]
	v_pk_fma_f32 v[166:167], v[166:167], v[164:165], v[170:171] op_sel_hi:[1,0,1]
	v_cvt_pk_f32_fp8_sdwa v[170:171], v160 src0_sel:WORD_1
	v_lshl_or_b32 v14, v16, 7, v1
	v_lshl_or_b32 v10, v12, 7, v1
	global_load_dwordx4 v[114:117], v6, s[4:5]
	global_load_dwordx4 v[130:133], v2, s[4:5]
	v_pk_fma_f32 v[170:171], v[170:171], v[164:165], v[174:175] op_sel_hi:[1,0,1]
	v_cvt_pk_f32_fp8_e32 v[174:175], v161
	v_cvt_pk_f32_fp8_sdwa v[160:161], v161 src0_sel:WORD_1
	v_lshl_or_b32 v6, v9, 7, v1
	v_lshl_or_b32 v2, v5, 7, v1
	v_pk_fma_f32 v[174:175], v[174:175], v[164:165], v[194:195] op_sel_hi:[1,0,1]
	v_pk_fma_f32 v[160:161], v[160:161], v[164:165], v[162:163] op_sel_hi:[1,0,1]
	v_cvt_pk_f32_fp8_e32 v[162:163], v138
	v_cvt_pk_f32_fp8_sdwa v[164:165], v138 src0_sel:WORD_1
	s_lshl_b64 s[6:7], s[14:15], 9
	global_load_dwordx4 v[78:81], v14, s[4:5]
	global_load_dwordx4 v[98:101], v10, s[4:5]
	v_pk_fma_f32 v[162:163], v[162:163], v[62:63], v[168:169] op_sel_hi:[1,0,1]
	v_cvt_pk_f32_fp8_e32 v[168:169], v139
	v_cvt_pk_f32_fp8_sdwa v[138:139], v139 src0_sel:WORD_1
	v_pk_fma_f32 v[164:165], v[164:165], v[62:63], v[172:173] op_sel_hi:[1,0,1]
	v_lshl_or_b32 v14, v17, 7, v1
	v_pk_fma_f32 v[168:169], v[168:169], v[62:63], v[176:177] op_sel_hi:[1,0,1]
	v_pk_fma_f32 v[138:139], v[138:139], v[62:63], v[158:159] op_sel_hi:[1,0,1]
	v_cvt_pk_f32_fp8_e32 v[158:159], v140
	v_lshl_or_b32 v10, v13, 7, v1
	global_load_dwordx4 v[118:121], v6, s[4:5]
	global_load_dwordx4 v[134:137], v2, s[4:5]
	v_pk_fma_f32 v[158:159], v[158:159], v[62:63], v[166:167] op_sel_hi:[1,0,1]
	v_cvt_pk_f32_fp8_sdwa v[166:167], v140 src0_sel:WORD_1
	v_lshl_add_u64 v[2:3], v[184:185], 0, s[6:7]
	s_lshl_b64 s[6:7], s[14:15], 12
	global_load_dwordx4 v[82:85], v14, s[4:5]
	global_load_dwordx4 v[102:105], v10, s[4:5]
	v_pk_fma_f32 v[166:167], v[166:167], v[62:63], v[170:171] op_sel_hi:[1,0,1]
	v_cvt_pk_f32_fp8_e32 v[170:171], v141
	v_cvt_pk_f32_fp8_sdwa v[140:141], v141 src0_sel:WORD_1
	global_load_dwordx4 v[142:145], v[2:3], off offset:48
	global_load_dwordx4 v[146:149], v[2:3], off offset:32
	global_load_dwordx4 v[150:153], v[2:3], off offset:16
	global_load_dwordx4 v[154:157], v[2:3], off
	v_lshl_add_u64 v[2:3], v[182:183], 0, s[6:7]
	v_pk_fma_f32 v[170:171], v[170:171], v[62:63], v[174:175] op_sel_hi:[1,0,1]
	v_pk_fma_f32 v[140:141], v[140:141], v[62:63], v[160:161] op_sel_hi:[1,0,1]
	v_cvt_pk_f32_fp8_e32 v[160:161], v94
	s_add_i32 s6, s11, s18
	s_min_i32 s6, s6, 0x3fff
	s_ashr_i32 s7, s6, 31
	v_pk_fma_f32 v[160:161], v[160:161], v[62:63], v[162:163] op_sel:[0,1,0]
	v_cvt_pk_f32_fp8_sdwa v[162:163], v94 src0_sel:WORD_1
	s_lshl_b64 s[28:29], s[6:7], 10
	v_lshl_add_u64 v[14:15], v[180:181], 0, s[28:29]
	global_load_dwordx2 v[188:189], v[2:3], off
	v_pk_fma_f32 v[162:163], v[162:163], v[62:63], v[164:165] op_sel:[0,1,0]
	v_cvt_pk_f32_fp8_e32 v[164:165], v95
	v_cvt_pk_f32_fp8_sdwa v[94:95], v95 src0_sel:WORD_1
	global_load_dwordx4 v[2:5], v[14:15], off offset:48
	global_load_dwordx4 v[6:9], v[14:15], off offset:32
	global_load_dwordx4 v[10:13], v[14:15], off offset:16
	s_nop 0
	global_load_dwordx4 v[14:17], v[14:15], off
	s_ashr_i32 s13, s12, 31
	v_pk_fma_f32 v[164:165], v[164:165], v[62:63], v[168:169] op_sel:[0,1,0]
; __device__ __forceinline__ f32x2 fp8x2_lo(unsigned w) { return __builtin_amdgcn_cvt_pk_f32_fp8(w, false); }
; __device__ __forceinline__ f32x2 fp8x2_hi(unsigned w) { return __builtin_amdgcn_cvt_pk_f32_fp8(w, true); }
; template <bool NT>
; __device__ __forceinline__ void peer_passB(const Args& a, const PeerWork w) {
;     ...
;         for (int k = 0; k < 16; ++k) {
;             const unsigned ww[4] = {vr[k].x, vr[k].y, vr[k].z, vr[k].w};
;             const float c = cf[k >> 2][k & 3]; const f32x2 c2 = {c, c};
; #pragma unroll
;             for (int wd = 0; wd < 4; ++wd) { acc[2 * wd] = __builtin_elementwise_fma(fp8x2_lo(ww[wd]), c2, acc[2 * wd]); acc[2 * wd + 1] = __builtin_elementwise_fma(fp8x2_hi(ww[wd]), c2, acc[2 * wd + 1]); }
	v_pk_fma_f32 v[94:95], v[94:95], v[62:63], v[138:139] op_sel:[0,1,0]
	v_cvt_pk_f32_fp8_e32 v[138:139], v96
	s_lshl_b64 s[12:13], s[12:13], 12
	s_add_i32 s18, s18, s22
	v_pk_fma_f32 v[138:139], v[138:139], v[62:63], v[158:159] op_sel:[0,1,0]
	v_cvt_pk_f32_fp8_sdwa v[158:159], v96 src0_sel:WORD_1
	s_cmpk_lt_i32 s18, 0x4000
	v_pk_fma_f32 v[158:159], v[158:159], v[62:63], v[166:167] op_sel:[0,1,0]
	v_cvt_pk_f32_fp8_e32 v[166:167], v97
	v_cvt_pk_f32_fp8_sdwa v[96:97], v97 src0_sel:WORD_1
	v_pk_fma_f32 v[166:167], v[166:167], v[62:63], v[170:171] op_sel:[0,1,0]
	v_pk_fma_f32 v[62:63], v[96:97], v[62:63], v[140:141] op_sel:[0,1,0]
	v_cvt_pk_f32_fp8_e32 v[96:97], v66
	v_cvt_pk_f32_fp8_sdwa v[140:141], v66 src0_sel:WORD_1
	v_pk_fma_f32 v[96:97], v[96:97], v[64:65], v[160:161] op_sel_hi:[1,0,1]
	v_cvt_pk_f32_fp8_e32 v[160:161], v67
	v_cvt_pk_f32_fp8_sdwa v[66:67], v67 src0_sel:WORD_1
	v_pk_fma_f32 v[140:141], v[140:141], v[64:65], v[162:163] op_sel_hi:[1,0,1]
	v_pk_fma_f32 v[160:161], v[160:161], v[64:65], v[164:165] op_sel_hi:[1,0,1]
	v_pk_fma_f32 v[66:67], v[66:67], v[64:65], v[94:95] op_sel_hi:[1,0,1]
	v_cvt_pk_f32_fp8_e32 v[94:95], v68
	v_pk_fma_f32 v[94:95], v[94:95], v[64:65], v[138:139] op_sel_hi:[1,0,1]
	v_cvt_pk_f32_fp8_sdwa v[138:139], v68 src0_sel:WORD_1
	v_pk_fma_f32 v[138:139], v[138:139], v[64:65], v[158:159] op_sel_hi:[1,0,1]
	v_cvt_pk_f32_fp8_e32 v[158:159], v69
	v_cvt_pk_f32_fp8_sdwa v[68:69], v69 src0_sel:WORD_1
	v_pk_fma_f32 v[158:159], v[158:159], v[64:65], v[166:167] op_sel_hi:[1,0,1]
	v_pk_fma_f32 v[62:63], v[68:69], v[64:65], v[62:63] op_sel_hi:[1,0,1]
	v_cvt_pk_f32_fp8_e32 v[68:69], v58
	v_mov_b32_e32 v64, v65
	v_pk_fma_f32 v[68:69], v[68:69], v[64:65], v[96:97] op_sel_hi:[1,0,1]
	v_cvt_pk_f32_fp8_sdwa v[96:97], v58 src0_sel:WORD_1
	v_pk_fma_f32 v[96:97], v[96:97], v[64:65], v[140:141] op_sel_hi:[1,0,1]
	v_cvt_pk_f32_fp8_e32 v[140:141], v59
	v_cvt_pk_f32_fp8_sdwa v[58:59], v59 src0_sel:WORD_1
	v_pk_fma_f32 v[140:141], v[140:141], v[64:65], v[160:161] op_sel_hi:[1,0,1]
	v_pk_fma_f32 v[58:59], v[58:59], v[64:65], v[66:67] op_sel_hi:[1,0,1]
	v_cvt_pk_f32_fp8_e32 v[66:67], v60
	v_pk_fma_f32 v[66:67], v[66:67], v[64:65], v[94:95] op_sel_hi:[1,0,1]
	v_cvt_pk_f32_fp8_sdwa v[94:95], v60 src0_sel:WORD_1
	v_pk_fma_f32 v[94:95], v[94:95], v[64:65], v[138:139] op_sel_hi:[1,0,1]
	v_cvt_pk_f32_fp8_e32 v[138:139], v61
	v_cvt_pk_f32_fp8_sdwa v[60:61], v61 src0_sel:WORD_1
	v_pk_fma_f32 v[138:139], v[138:139], v[64:65], v[158:159] op_sel_hi:[1,0,1]
	v_pk_fma_f32 v[60:61], v[60:61], v[64:65], v[62:63] op_sel_hi:[1,0,1]
	v_cvt_pk_f32_fp8_e32 v[62:63], v54
	v_cvt_pk_f32_fp8_sdwa v[64:65], v54 src0_sel:WORD_1
	v_pk_fma_f32 v[62:63], v[62:63], v[38:39], v[68:69] op_sel_hi:[1,0,1]
	v_cvt_pk_f32_fp8_e32 v[68:69], v55
	v_cvt_pk_f32_fp8_sdwa v[54:55], v55 src0_sel:WORD_1
	v_pk_fma_f32 v[64:65], v[64:65], v[38:39], v[96:97] op_sel_hi:[1,0,1]
	v_pk_fma_f32 v[68:69], v[68:69], v[38:39], v[140:141] op_sel_hi:[1,0,1]
	v_pk_fma_f32 v[54:55], v[54:55], v[38:39], v[58:59] op_sel_hi:[1,0,1]
	v_cvt_pk_f32_fp8_e32 v[58:59], v56
	v_pk_fma_f32 v[58:59], v[58:59], v[38:39], v[66:67] op_sel_hi:[1,0,1]
	v_cvt_pk_f32_fp8_sdwa v[66:67], v56 src0_sel:WORD_1
	v_pk_fma_f32 v[66:67], v[66:67], v[38:39], v[94:95] op_sel_hi:[1,0,1]
	v_cvt_pk_f32_fp8_e32 v[94:95], v57
	v_cvt_pk_f32_fp8_sdwa v[56:57], v57 src0_sel:WORD_1
	v_pk_fma_f32 v[94:95], v[94:95], v[38:39], v[138:139] op_sel_hi:[1,0,1]
	v_pk_fma_f32 v[56:57], v[56:57], v[38:39], v[60:61] op_sel_hi:[1,0,1]
	v_cvt_pk_f32_fp8_e32 v[60:61], v50
	v_pk_fma_f32 v[60:61], v[60:61], v[38:39], v[62:63] op_sel:[0,1,0]
	v_cvt_pk_f32_fp8_sdwa v[62:63], v50 src0_sel:WORD_1
	v_pk_fma_f32 v[62:63], v[62:63], v[38:39], v[64:65] op_sel:[0,1,0]
	v_cvt_pk_f32_fp8_e32 v[64:65], v51
	v_cvt_pk_f32_fp8_sdwa v[50:51], v51 src0_sel:WORD_1
	v_pk_fma_f32 v[64:65], v[64:65], v[38:39], v[68:69] op_sel:[0,1,0]
	v_pk_fma_f32 v[50:51], v[50:51], v[38:39], v[54:55] op_sel:[0,1,0]
	v_cvt_pk_f32_fp8_e32 v[54:55], v52
	v_pk_fma_f32 v[54:55], v[54:55], v[38:39], v[58:59] op_sel:[0,1,0]
	v_cvt_pk_f32_fp8_sdwa v[58:59], v52 src0_sel:WORD_1
	v_pk_fma_f32 v[58:59], v[58:59], v[38:39], v[66:67] op_sel:[0,1,0]
	v_cvt_pk_f32_fp8_e32 v[66:67], v53
	v_cvt_pk_f32_fp8_sdwa v[52:53], v53 src0_sel:WORD_1
	v_pk_fma_f32 v[66:67], v[66:67], v[38:39], v[94:95] op_sel:[0,1,0]
	v_pk_fma_f32 v[38:39], v[52:53], v[38:39], v[56:57] op_sel:[0,1,0]
	v_cvt_pk_f32_fp8_e32 v[52:53], v46
	v_cvt_pk_f32_fp8_sdwa v[56:57], v46 src0_sel:WORD_1
	v_pk_fma_f32 v[52:53], v[52:53], v[40:41], v[60:61] op_sel_hi:[1,0,1]
	v_cvt_pk_f32_fp8_e32 v[60:61], v47
	v_cvt_pk_f32_fp8_sdwa v[46:47], v47 src0_sel:WORD_1
	v_pk_fma_f32 v[56:57], v[56:57], v[40:41], v[62:63] op_sel_hi:[1,0,1]
	v_pk_fma_f32 v[60:61], v[60:61], v[40:41], v[64:65] op_sel_hi:[1,0,1]
	v_pk_fma_f32 v[46:47], v[46:47], v[40:41], v[50:51] op_sel_hi:[1,0,1]
	v_cvt_pk_f32_fp8_e32 v[50:51], v48
	v_pk_fma_f32 v[50:51], v[50:51], v[40:41], v[54:55] op_sel_hi:[1,0,1]
	v_cvt_pk_f32_fp8_sdwa v[54:55], v48 src0_sel:WORD_1
	v_pk_fma_f32 v[54:55], v[54:55], v[40:41], v[58:59] op_sel_hi:[1,0,1]
	v_cvt_pk_f32_fp8_e32 v[58:59], v49
	v_cvt_pk_f32_fp8_sdwa v[48:49], v49 src0_sel:WORD_1
	v_pk_fma_f32 v[58:59], v[58:59], v[40:41], v[66:67] op_sel_hi:[1,0,1]
	v_pk_fma_f32 v[38:39], v[48:49], v[40:41], v[38:39] op_sel_hi:[1,0,1]
	v_cvt_pk_f32_fp8_e32 v[48:49], v42
	v_mov_b32_e32 v40, v41
	v_pk_fma_f32 v[48:49], v[48:49], v[40:41], v[52:53] op_sel_hi:[1,0,1]
	v_cvt_pk_f32_fp8_sdwa v[52:53], v42 src0_sel:WORD_1
	v_pk_fma_f32 v[52:53], v[52:53], v[40:41], v[56:57] op_sel_hi:[1,0,1]
	v_cvt_pk_f32_fp8_e32 v[56:57], v43
	v_cvt_pk_f32_fp8_sdwa v[42:43], v43 src0_sel:WORD_1
; template <int CTRL> __device__ __forceinline__ float dpp_f(float x) { return __uint_as_float((unsigned)__builtin_amdgcn_update_dpp(0, (int)__float_as_uint(x), CTRL, 0xf, 0xf, false)); }
; __device__ __forceinline__ f32x2 fp8x2_lo(unsigned w) { return __builtin_amdgcn_cvt_pk_f32_fp8(w, false); }
; __device__ __forceinline__ f32x2 fp8x2_hi(unsigned w) { return __builtin_amdgcn_cvt_pk_f32_fp8(w, true); }
; template <bool NT>
; __device__ __forceinline__ void peer_passB(const Args& a, const PeerWork w) {
;     ...
;         for (int k = 0; k < 16; ++k) {
;             const unsigned ww[4] = {vr[k].x, vr[k].y, vr[k].z, vr[k].w};
;             const float c = cf[k >> 2][k & 3]; const f32x2 c2 = {c, c};
; #pragma unroll
;             for (int wd = 0; wd < 4; ++wd) { acc[2 * wd] = __builtin_elementwise_fma(fp8x2_lo(ww[wd]), c2, acc[2 * wd]); acc[2 * wd + 1] = __builtin_elementwise_fma(fp8x2_hi(ww[wd]), c2, acc[2 * wd + 1]); }
;         }
;         float w8[8], w4[4], w2[2];
; #pragma unroll
;         for (int m = 0; m < 8; ++m) { const auto sw = __builtin_amdgcn_permlane32_swap(__float_as_uint(acc[m >> 1][m & 1]), __float_as_uint(acc[(m + 8) >> 1][m & 1]), false, false); w8[m] = __uint_as_float(sw[0]) + __uint_as_float(sw[1]); }
; #pragma unroll
;         for (int m = 0; m < 4; ++m) { const auto sw = __builtin_amdgcn_permlane16_swap(__float_as_uint(w8[m]), __float_as_uint(w8[m + 4]), false, false); w4[m] = __uint_as_float(sw[0]) + __uint_as_float(sw[1]); }
;         { const bool up = (lane & 8) != 0;
; #pragma unroll
;           for (int m = 0; m < 2; ++m) { const float keep = up ? w4[m + 2] : w4[m], send = up ? w4[m] : w4[m + 2]; w2[m] = keep + dpp_f<0x128>(send); } }
;         *(f32x2*)(Y + (size_t)t * DM) = (f32x2){hv[0] + w2[0], hv[1] + w2[1]};
;         if (q + qs > ql) break;
; #pragma unroll
;         for (int k = 0; k < 16; ++k) vr[k] = vrn[k];
; #pragma unroll
;         for (int qq = 0; qq < 4; ++qq) cf[qq] = cfn[qq];
;         hv = hn;
;         t = t1; t1 = t2;
	v_pk_fma_f32 v[56:57], v[56:57], v[40:41], v[60:61] op_sel_hi:[1,0,1]
	v_pk_fma_f32 v[42:43], v[42:43], v[40:41], v[46:47] op_sel_hi:[1,0,1]
	v_cvt_pk_f32_fp8_e32 v[46:47], v44
	v_pk_fma_f32 v[46:47], v[46:47], v[40:41], v[50:51] op_sel_hi:[1,0,1]
	v_cvt_pk_f32_fp8_sdwa v[50:51], v44 src0_sel:WORD_1
	v_pk_fma_f32 v[50:51], v[50:51], v[40:41], v[54:55] op_sel_hi:[1,0,1]
	v_cvt_pk_f32_fp8_e32 v[54:55], v45
	v_cvt_pk_f32_fp8_sdwa v[44:45], v45 src0_sel:WORD_1
	v_pk_fma_f32 v[54:55], v[54:55], v[40:41], v[58:59] op_sel_hi:[1,0,1]
	v_pk_fma_f32 v[38:39], v[44:45], v[40:41], v[38:39] op_sel_hi:[1,0,1]
	v_cvt_pk_f32_fp8_e32 v[40:41], v34
	v_cvt_pk_f32_fp8_sdwa v[44:45], v34 src0_sel:WORD_1
	v_pk_fma_f32 v[40:41], v[40:41], v[22:23], v[48:49] op_sel_hi:[1,0,1]
	v_cvt_pk_f32_fp8_e32 v[48:49], v35
	v_cvt_pk_f32_fp8_sdwa v[34:35], v35 src0_sel:WORD_1
	v_pk_fma_f32 v[44:45], v[44:45], v[22:23], v[52:53] op_sel_hi:[1,0,1]
	v_pk_fma_f32 v[48:49], v[48:49], v[22:23], v[56:57] op_sel_hi:[1,0,1]
	v_pk_fma_f32 v[34:35], v[34:35], v[22:23], v[42:43] op_sel_hi:[1,0,1]
	v_cvt_pk_f32_fp8_e32 v[42:43], v36
	v_pk_fma_f32 v[42:43], v[42:43], v[22:23], v[46:47] op_sel_hi:[1,0,1]
	v_cvt_pk_f32_fp8_sdwa v[46:47], v36 src0_sel:WORD_1
	v_pk_fma_f32 v[46:47], v[46:47], v[22:23], v[50:51] op_sel_hi:[1,0,1]
	v_cvt_pk_f32_fp8_e32 v[50:51], v37
	v_cvt_pk_f32_fp8_sdwa v[36:37], v37 src0_sel:WORD_1
	v_pk_fma_f32 v[50:51], v[50:51], v[22:23], v[54:55] op_sel_hi:[1,0,1]
	v_pk_fma_f32 v[36:37], v[36:37], v[22:23], v[38:39] op_sel_hi:[1,0,1]
	v_cvt_pk_f32_fp8_e32 v[38:39], v30
	v_pk_fma_f32 v[38:39], v[38:39], v[22:23], v[40:41] op_sel:[0,1,0]
	v_cvt_pk_f32_fp8_sdwa v[40:41], v30 src0_sel:WORD_1
	v_pk_fma_f32 v[40:41], v[40:41], v[22:23], v[44:45] op_sel:[0,1,0]
	v_cvt_pk_f32_fp8_e32 v[44:45], v31
	v_cvt_pk_f32_fp8_sdwa v[30:31], v31 src0_sel:WORD_1
	v_pk_fma_f32 v[44:45], v[44:45], v[22:23], v[48:49] op_sel:[0,1,0]
	v_pk_fma_f32 v[30:31], v[30:31], v[22:23], v[34:35] op_sel:[0,1,0]
	v_cvt_pk_f32_fp8_e32 v[34:35], v32
	v_pk_fma_f32 v[34:35], v[34:35], v[22:23], v[42:43] op_sel:[0,1,0]
	v_cvt_pk_f32_fp8_sdwa v[42:43], v32 src0_sel:WORD_1
	v_pk_fma_f32 v[42:43], v[42:43], v[22:23], v[46:47] op_sel:[0,1,0]
	v_cvt_pk_f32_fp8_e32 v[46:47], v33
	v_cvt_pk_f32_fp8_sdwa v[32:33], v33 src0_sel:WORD_1
	v_pk_fma_f32 v[46:47], v[46:47], v[22:23], v[50:51] op_sel:[0,1,0]
	v_pk_fma_f32 v[22:23], v[32:33], v[22:23], v[36:37] op_sel:[0,1,0]
	v_cvt_pk_f32_fp8_e32 v[32:33], v26
	v_cvt_pk_f32_fp8_sdwa v[36:37], v26 src0_sel:WORD_1
	v_pk_fma_f32 v[32:33], v[32:33], v[24:25], v[38:39] op_sel_hi:[1,0,1]
	v_cvt_pk_f32_fp8_e32 v[38:39], v27
	v_cvt_pk_f32_fp8_sdwa v[26:27], v27 src0_sel:WORD_1
	v_pk_fma_f32 v[36:37], v[36:37], v[24:25], v[40:41] op_sel_hi:[1,0,1]
	v_cvt_pk_f32_fp8_e32 v[40:41], v29
	v_pk_fma_f32 v[38:39], v[38:39], v[24:25], v[44:45] op_sel_hi:[1,0,1]
	v_pk_fma_f32 v[26:27], v[26:27], v[24:25], v[30:31] op_sel_hi:[1,0,1]
	v_cvt_pk_f32_fp8_e32 v[30:31], v28
	v_pk_fma_f32 v[40:41], v[40:41], v[24:25], v[46:47] op_sel_hi:[1,0,1]
	v_pk_fma_f32 v[30:31], v[30:31], v[24:25], v[34:35] op_sel_hi:[1,0,1]
	v_cvt_pk_f32_fp8_sdwa v[34:35], v28 src0_sel:WORD_1
	v_cvt_pk_f32_fp8_sdwa v[28:29], v29 src0_sel:WORD_1
	v_pk_fma_f32 v[34:35], v[34:35], v[24:25], v[42:43] op_sel_hi:[1,0,1]
	v_pk_fma_f32 v[22:23], v[28:29], v[24:25], v[22:23] op_sel_hi:[1,0,1]
	v_cvt_pk_f32_fp8_e32 v[28:29], v18
	v_mov_b32_e32 v24, v25
	v_pk_fma_f32 v[28:29], v[28:29], v[24:25], v[32:33] op_sel_hi:[1,0,1]
	v_cvt_pk_f32_fp8_sdwa v[32:33], v18 src0_sel:WORD_1
	v_pk_fma_f32 v[32:33], v[32:33], v[24:25], v[36:37] op_sel_hi:[1,0,1]
	v_cvt_pk_f32_fp8_e32 v[36:37], v19
	v_cvt_pk_f32_fp8_sdwa v[18:19], v19 src0_sel:WORD_1
	v_pk_fma_f32 v[36:37], v[36:37], v[24:25], v[38:39] op_sel_hi:[1,0,1]
	v_pk_fma_f32 v[18:19], v[18:19], v[24:25], v[26:27] op_sel_hi:[1,0,1]
	v_cvt_pk_f32_fp8_e32 v[26:27], v20
	v_pk_fma_f32 v[26:27], v[26:27], v[24:25], v[30:31] op_sel_hi:[1,0,1]
	v_cvt_pk_f32_fp8_sdwa v[30:31], v20 src0_sel:WORD_1
	s_nop 0
	v_permlane32_swap_b32_e32 v28, v26
	v_permlane32_swap_b32_e32 v29, v27
	v_pk_fma_f32 v[30:31], v[30:31], v[24:25], v[34:35] op_sel_hi:[1,0,1]
	v_cvt_pk_f32_fp8_e32 v[34:35], v21
	v_cvt_pk_f32_fp8_sdwa v[20:21], v21 src0_sel:WORD_1
	v_permlane32_swap_b32_e32 v32, v30
	v_pk_fma_f32 v[34:35], v[34:35], v[24:25], v[40:41] op_sel_hi:[1,0,1]
	v_pk_fma_f32 v[20:21], v[20:21], v[24:25], v[22:23] op_sel_hi:[1,0,1]
	v_permlane32_swap_b32_e32 v33, v31
	v_permlane32_swap_b32_e32 v36, v34
	v_permlane32_swap_b32_e32 v37, v35
	v_permlane32_swap_b32_e32 v18, v20
	v_permlane32_swap_b32_e32 v19, v21
	v_add_f32_e32 v22, v28, v26
	v_add_f32_e32 v23, v29, v27
	v_add_f32_e32 v24, v32, v30
	v_add_f32_e32 v25, v33, v31
	v_add_f32_e32 v26, v36, v34
	v_add_f32_e32 v27, v37, v35
	v_add_f32_e32 v18, v18, v20
	v_add_f32_e32 v19, v19, v21
	v_permlane16_swap_b32_e32 v22, v26
	v_permlane16_swap_b32_e32 v23, v27
	v_permlane16_swap_b32_e32 v24, v18
	v_permlane16_swap_b32_e32 v25, v19
	v_pk_add_f32 v[20:21], v[22:23], v[26:27]
	v_pk_add_f32 v[18:19], v[24:25], v[18:19]
	v_mov_b32_e32 v22, 0
	v_cndmask_b32_e32 v23, v20, v18, vcc
	v_cndmask_b32_e32 v24, v18, v20, vcc
	v_cndmask_b32_e32 v18, v21, v19, vcc
	v_mov_b32_dpp v22, v23 row_ror:8 row_mask:0xf bank_mask:0xf
	v_mov_b32_e32 v23, 0
	v_cndmask_b32_e32 v25, v19, v21, vcc
	v_lshl_add_u64 v[20:21], v[186:187], 0, s[12:13]
	v_mov_b32_dpp v23, v18 row_ror:8 row_mask:0xf bank_mask:0xf
	v_pk_add_f32 v[18:19], v[24:25], v[22:23]
	v_pk_add_f32 v[18:19], v[190:191], v[18:19]
	global_store_dwordx2 v[20:21], v[18:19], off
	s_mov_b32 s12, s14
	s_cbranch_scc0 .LBB0_1588
; __device__ __forceinline__ f32x2 fp8x2_lo(unsigned w) { return __builtin_amdgcn_cvt_pk_f32_fp8(w, false); }
; __device__ __forceinline__ f32x2 fp8x2_hi(unsigned w) { return __builtin_amdgcn_cvt_pk_f32_fp8(w, true); }
; #define PB_IDS(T) do { const unsigned* kp_ = KP + (size_t)(T) * 256; _Pragma("unroll") for (int qq = 0; qq < 4; ++qq) idv[qq] = *(const u32x4*)(kp_ + 4 * qq); } while (0)
; template <bool NT>
; __device__ __forceinline__ void peer_passB(const Args& a, const PeerWork w) {
;     ...
;     int t = peer_tok(w, q), t1 = peer_tok(w, min(q + qs, ql));
;     PB_IDS(t);
;     PB_GATHER(t, vr, cf, hv);
;     PB_IDS(t1);
; #pragma unroll 1
;     for (;; q += qs) {
;         u32x4 vrn[16]; f32x4 cfn[4]; f32x2 hn;
;         PB_GATHER(t1, vrn, cfn, hn);
;         const int t2 = peer_tok(w, min(q + 2 * qs, ql));
;         PB_IDS(t2);
;         f32x2 acc[8];
; #pragma unroll
;         for (int m = 0; m < 8; ++m) acc[m] = (f32x2){0.f, 0.f};
; #pragma unroll
;         for (int k = 0; k < 16; ++k) {
;             const unsigned ww[4] = {vr[k].x, vr[k].y, vr[k].z, vr[k].w};
;             const float c = cf[k >> 2][k & 3]; const f32x2 c2 = {c, c};
; #pragma unroll
;             for (int wd = 0; wd < 4; ++wd) { acc[2 * wd] = __builtin_elementwise_fma(fp8x2_lo(ww[wd]), c2, acc[2 * wd]); acc[2 * wd + 1] = __builtin_elementwise_fma(fp8x2_hi(ww[wd]), c2, acc[2 * wd + 1]); }
	s_waitcnt vmcnt(23)
	v_cvt_pk_f32_fp8_e32 v[192:193], v70
	s_waitcnt vmcnt(19)
	v_cvt_pk_f32_fp8_e32 v[204:205], v74
	v_cvt_pk_f32_fp8_sdwa v[194:195], v70 src0_sel:WORD_1
	v_cvt_pk_f32_fp8_e32 v[196:197], v71
	s_waitcnt vmcnt(6)
	v_pk_fma_f32 v[192:193], v[192:193], v[154:155], 0 op_sel_hi:[1,0,0]
	v_cvt_pk_f32_fp8_sdwa v[70:71], v71 src0_sel:WORD_1
	v_pk_fma_f32 v[192:193], v[204:205], v[154:155], v[192:193] op_sel:[0,1,0]
	v_cvt_pk_f32_fp8_sdwa v[204:205], v74 src0_sel:WORD_1
	v_pk_fma_f32 v[194:195], v[194:195], v[154:155], 0 op_sel_hi:[1,0,0]
	v_pk_fma_f32 v[70:71], v[70:71], v[154:155], 0 op_sel_hi:[1,0,0]
	v_cvt_pk_f32_fp8_e32 v[198:199], v72
	v_pk_fma_f32 v[194:195], v[204:205], v[154:155], v[194:195] op_sel:[0,1,0]
	v_cvt_pk_f32_fp8_e32 v[204:205], v75
	v_cvt_pk_f32_fp8_sdwa v[74:75], v75 src0_sel:WORD_1
	v_pk_fma_f32 v[198:199], v[198:199], v[154:155], 0 op_sel_hi:[1,0,0]
	v_cvt_pk_f32_fp8_sdwa v[200:201], v72 src0_sel:WORD_1
	v_cvt_pk_f32_fp8_e32 v[202:203], v73
	v_pk_fma_f32 v[74:75], v[74:75], v[154:155], v[70:71] op_sel:[0,1,0]
	v_cvt_pk_f32_fp8_e32 v[70:71], v76
	v_pk_fma_f32 v[200:201], v[200:201], v[154:155], 0 op_sel_hi:[1,0,0]
	v_cvt_pk_f32_fp8_sdwa v[72:73], v73 src0_sel:WORD_1
	v_pk_fma_f32 v[196:197], v[196:197], v[154:155], 0 op_sel_hi:[1,0,0]
	v_pk_fma_f32 v[70:71], v[70:71], v[154:155], v[198:199] op_sel:[0,1,0]
	v_cvt_pk_f32_fp8_sdwa v[198:199], v76 src0_sel:WORD_1
	v_pk_fma_f32 v[202:203], v[202:203], v[154:155], 0 op_sel_hi:[1,0,0]
	v_pk_fma_f32 v[72:73], v[72:73], v[154:155], 0 op_sel_hi:[1,0,0]
	v_pk_fma_f32 v[196:197], v[204:205], v[154:155], v[196:197] op_sel:[0,1,0]
	v_pk_fma_f32 v[198:199], v[198:199], v[154:155], v[200:201] op_sel:[0,1,0]
	v_cvt_pk_f32_fp8_e32 v[200:201], v77
	v_cvt_pk_f32_fp8_sdwa v[76:77], v77 src0_sel:WORD_1
	s_waitcnt vmcnt(3)
	v_lshl_or_b32 v6, v6, 7, v1
	v_lshl_or_b32 v2, v2, 7, v1
	v_pk_fma_f32 v[200:201], v[200:201], v[154:155], v[202:203] op_sel:[0,1,0]
	v_pk_fma_f32 v[154:155], v[76:77], v[154:155], v[72:73] op_sel:[0,1,0]
	v_cvt_pk_f32_fp8_e32 v[76:77], v78
	v_cvt_pk_f32_fp8_sdwa v[72:73], v78 src0_sel:WORD_1
	s_waitcnt vmcnt(1)
	v_lshl_or_b32 v14, v14, 7, v1
	v_lshl_or_b32 v10, v10, 7, v1
	v_pk_fma_f32 v[76:77], v[76:77], v[156:157], v[192:193] op_sel_hi:[1,0,1]
	v_cvt_pk_f32_fp8_e32 v[192:193], v79
	v_cvt_pk_f32_fp8_sdwa v[78:79], v79 src0_sel:WORD_1
	v_pk_fma_f32 v[72:73], v[72:73], v[156:157], v[194:195] op_sel_hi:[1,0,1]
	v_cvt_pk_f32_fp8_e32 v[194:195], v81
	v_pk_fma_f32 v[192:193], v[192:193], v[156:157], v[196:197] op_sel_hi:[1,0,1]
	v_pk_fma_f32 v[78:79], v[78:79], v[156:157], v[74:75] op_sel_hi:[1,0,1]
	v_cvt_pk_f32_fp8_e32 v[74:75], v80
	v_pk_fma_f32 v[194:195], v[194:195], v[156:157], v[200:201] op_sel_hi:[1,0,1]
	global_load_dwordx4 v[54:57], v6, s[4:5]
	global_load_dwordx4 v[34:37], v2, s[4:5]
	v_pk_fma_f32 v[74:75], v[74:75], v[156:157], v[70:71] op_sel_hi:[1,0,1]
	v_cvt_pk_f32_fp8_sdwa v[70:71], v80 src0_sel:WORD_1
	v_cvt_pk_f32_fp8_sdwa v[80:81], v81 src0_sel:WORD_1
	v_lshl_or_b32 v6, v7, 7, v1
	v_lshl_or_b32 v2, v3, 7, v1
	v_pk_fma_f32 v[70:71], v[70:71], v[156:157], v[198:199] op_sel_hi:[1,0,1]
	v_pk_fma_f32 v[154:155], v[80:81], v[156:157], v[154:155] op_sel_hi:[1,0,1]
	v_cvt_pk_f32_fp8_e32 v[80:81], v82
	v_mov_b32_e32 v156, v157
	s_mov_b32 s14, s6
	global_load_dwordx4 v[174:177], v14, s[4:5]
	global_load_dwordx4 v[138:141], v10, s[4:5]
	v_pk_fma_f32 v[80:81], v[80:81], v[156:157], v[76:77] op_sel_hi:[1,0,1]
	v_cvt_pk_f32_fp8_sdwa v[76:77], v82 src0_sel:WORD_1
	v_lshl_or_b32 v14, v15, 7, v1
	v_lshl_or_b32 v10, v11, 7, v1
	global_load_dwordx4 v[50:53], v6, s[4:5]
	global_load_dwordx4 v[30:33], v2, s[4:5]
	v_pk_fma_f32 v[76:77], v[76:77], v[156:157], v[72:73] op_sel_hi:[1,0,1]
	v_cvt_pk_f32_fp8_e32 v[72:73], v83
	v_cvt_pk_f32_fp8_sdwa v[82:83], v83 src0_sel:WORD_1
	v_lshl_or_b32 v6, v8, 7, v1
	v_lshl_or_b32 v2, v4, 7, v1
	v_pk_fma_f32 v[72:73], v[72:73], v[156:157], v[192:193] op_sel_hi:[1,0,1]
	v_pk_fma_f32 v[82:83], v[82:83], v[156:157], v[78:79] op_sel_hi:[1,0,1]
	v_cvt_pk_f32_fp8_e32 v[78:79], v84
	s_ashr_i32 s15, s6, 31
	global_load_dwordx4 v[170:173], v14, s[4:5]
	global_load_dwordx4 v[94:97], v10, s[4:5]
	v_pk_fma_f32 v[78:79], v[78:79], v[156:157], v[74:75] op_sel_hi:[1,0,1]
	v_cvt_pk_f32_fp8_sdwa v[74:75], v84 src0_sel:WORD_1
	v_lshl_or_b32 v14, v16, 7, v1
	v_lshl_or_b32 v10, v12, 7, v1
	global_load_dwordx4 v[46:49], v6, s[4:5]
	global_load_dwordx4 v[26:29], v2, s[4:5]
	v_pk_fma_f32 v[74:75], v[74:75], v[156:157], v[70:71] op_sel_hi:[1,0,1]
	v_cvt_pk_f32_fp8_e32 v[70:71], v85
	v_cvt_pk_f32_fp8_sdwa v[84:85], v85 src0_sel:WORD_1
	v_lshl_or_b32 v6, v9, 7, v1
	v_lshl_or_b32 v2, v5, 7, v1
	v_pk_fma_f32 v[70:71], v[70:71], v[156:157], v[194:195] op_sel_hi:[1,0,1]
	v_pk_fma_f32 v[84:85], v[84:85], v[156:157], v[154:155] op_sel_hi:[1,0,1]
	v_cvt_pk_f32_fp8_e32 v[154:155], v86
	v_cvt_pk_f32_fp8_sdwa v[156:157], v86 src0_sel:WORD_1
	s_lshl_b64 s[6:7], s[14:15], 9
	global_load_dwordx4 v[166:169], v14, s[4:5]
	global_load_dwordx4 v[66:69], v10, s[4:5]
	v_pk_fma_f32 v[154:155], v[154:155], v[150:151], v[80:81] op_sel_hi:[1,0,1]
	v_cvt_pk_f32_fp8_e32 v[80:81], v87
	v_cvt_pk_f32_fp8_sdwa v[86:87], v87 src0_sel:WORD_1
	v_pk_fma_f32 v[156:157], v[156:157], v[150:151], v[76:77] op_sel_hi:[1,0,1]
	v_lshl_or_b32 v14, v17, 7, v1
	v_pk_fma_f32 v[80:81], v[80:81], v[150:151], v[72:73] op_sel_hi:[1,0,1]
	v_pk_fma_f32 v[86:87], v[86:87], v[150:151], v[82:83] op_sel_hi:[1,0,1]
	v_cvt_pk_f32_fp8_e32 v[82:83], v88
	v_lshl_or_b32 v10, v13, 7, v1
	global_load_dwordx4 v[42:45], v6, s[4:5]
	global_load_dwordx4 v[18:21], v2, s[4:5]
	v_pk_fma_f32 v[82:83], v[82:83], v[150:151], v[78:79] op_sel_hi:[1,0,1]
; __device__ __forceinline__ f32x2 fp8x2_lo(unsigned w) { return __builtin_amdgcn_cvt_pk_f32_fp8(w, false); }
; __device__ __forceinline__ f32x2 fp8x2_hi(unsigned w) { return __builtin_amdgcn_cvt_pk_f32_fp8(w, true); }
; #define PB_IDS(T) do { const unsigned* kp_ = KP + (size_t)(T) * 256; _Pragma("unroll") for (int qq = 0; qq < 4; ++qq) idv[qq] = *(const u32x4*)(kp_ + 4 * qq); } while (0)
; template <bool NT>
; __device__ __forceinline__ void peer_passB(const Args& a, const PeerWork w) {
;     ...
;     int t = peer_tok(w, q), t1 = peer_tok(w, min(q + qs, ql));
;     PB_IDS(t);
;     PB_GATHER(t, vr, cf, hv);
;     PB_IDS(t1);
; #pragma unroll 1
;     for (;; q += qs) {
;         u32x4 vrn[16]; f32x4 cfn[4]; f32x2 hn;
;         PB_GATHER(t1, vrn, cfn, hn);
;         const int t2 = peer_tok(w, min(q + 2 * qs, ql));
;         PB_IDS(t2);
;         f32x2 acc[8];
; #pragma unroll
;         for (int m = 0; m < 8; ++m) acc[m] = (f32x2){0.f, 0.f};
; #pragma unroll
;         for (int k = 0; k < 16; ++k) {
;             const unsigned ww[4] = {vr[k].x, vr[k].y, vr[k].z, vr[k].w};
;             const float c = cf[k >> 2][k & 3]; const f32x2 c2 = {c, c};
; #pragma unroll
;             for (int wd = 0; wd < 4; ++wd) { acc[2 * wd] = __builtin_elementwise_fma(fp8x2_lo(ww[wd]), c2, acc[2 * wd]); acc[2 * wd + 1] = __builtin_elementwise_fma(fp8x2_hi(ww[wd]), c2, acc[2 * wd + 1]); }
	v_cvt_pk_f32_fp8_sdwa v[78:79], v88 src0_sel:WORD_1
	v_lshl_add_u64 v[2:3], v[184:185], 0, s[6:7]
	s_lshl_b64 s[6:7], s[14:15], 12
	global_load_dwordx4 v[158:161], v14, s[4:5]
	global_load_dwordx4 v[58:61], v10, s[4:5]
	v_pk_fma_f32 v[78:79], v[78:79], v[150:151], v[74:75] op_sel_hi:[1,0,1]
	v_cvt_pk_f32_fp8_e32 v[74:75], v89
	v_cvt_pk_f32_fp8_sdwa v[88:89], v89 src0_sel:WORD_1
	global_load_dwordx4 v[22:25], v[2:3], off offset:48
	global_load_dwordx4 v[38:41], v[2:3], off offset:32
	global_load_dwordx4 v[62:65], v[2:3], off offset:16
	global_load_dwordx4 v[162:165], v[2:3], off
	v_lshl_add_u64 v[2:3], v[182:183], 0, s[6:7]
	v_pk_fma_f32 v[74:75], v[74:75], v[150:151], v[70:71] op_sel_hi:[1,0,1]
	v_pk_fma_f32 v[88:89], v[88:89], v[150:151], v[84:85] op_sel_hi:[1,0,1]
	v_cvt_pk_f32_fp8_e32 v[84:85], v90
	s_add_i32 s6, s11, s18
	s_min_i32 s6, s6, 0x3fff
	s_ashr_i32 s7, s6, 31
	v_pk_fma_f32 v[84:85], v[84:85], v[150:151], v[154:155] op_sel:[0,1,0]
	v_cvt_pk_f32_fp8_sdwa v[154:155], v90 src0_sel:WORD_1
	s_lshl_b64 s[28:29], s[6:7], 10
	v_lshl_add_u64 v[14:15], v[180:181], 0, s[28:29]
	global_load_dwordx2 v[190:191], v[2:3], off
	v_pk_fma_f32 v[154:155], v[154:155], v[150:151], v[156:157] op_sel:[0,1,0]
	v_cvt_pk_f32_fp8_e32 v[156:157], v91
	v_cvt_pk_f32_fp8_sdwa v[90:91], v91 src0_sel:WORD_1
	global_load_dwordx4 v[2:5], v[14:15], off offset:48
	global_load_dwordx4 v[6:9], v[14:15], off offset:32
	global_load_dwordx4 v[10:13], v[14:15], off offset:16
	s_nop 0
	global_load_dwordx4 v[14:17], v[14:15], off
	s_ashr_i32 s13, s12, 31
	v_pk_fma_f32 v[156:157], v[156:157], v[150:151], v[80:81] op_sel:[0,1,0]
	v_pk_fma_f32 v[90:91], v[90:91], v[150:151], v[86:87] op_sel:[0,1,0]
	v_cvt_pk_f32_fp8_e32 v[86:87], v92
	s_lshl_b64 s[12:13], s[12:13], 12
	s_add_i32 s18, s18, s22
	v_pk_fma_f32 v[86:87], v[86:87], v[150:151], v[82:83] op_sel:[0,1,0]
	v_cvt_pk_f32_fp8_sdwa v[82:83], v92 src0_sel:WORD_1
	s_cmpk_lt_i32 s18, 0x4000
	v_pk_fma_f32 v[82:83], v[82:83], v[150:151], v[78:79] op_sel:[0,1,0]
	v_cvt_pk_f32_fp8_e32 v[78:79], v93
	v_cvt_pk_f32_fp8_sdwa v[92:93], v93 src0_sel:WORD_1
	v_pk_fma_f32 v[78:79], v[78:79], v[150:151], v[74:75] op_sel:[0,1,0]
	v_pk_fma_f32 v[150:151], v[92:93], v[150:151], v[88:89] op_sel:[0,1,0]
	v_cvt_pk_f32_fp8_e32 v[92:93], v98
	v_cvt_pk_f32_fp8_sdwa v[88:89], v98 src0_sel:WORD_1
	v_pk_fma_f32 v[92:93], v[92:93], v[152:153], v[84:85] op_sel_hi:[1,0,1]
	v_cvt_pk_f32_fp8_e32 v[84:85], v99
	v_cvt_pk_f32_fp8_sdwa v[98:99], v99 src0_sel:WORD_1
	v_pk_fma_f32 v[88:89], v[88:89], v[152:153], v[154:155] op_sel_hi:[1,0,1]
	v_pk_fma_f32 v[84:85], v[84:85], v[152:153], v[156:157] op_sel_hi:[1,0,1]
	v_pk_fma_f32 v[98:99], v[98:99], v[152:153], v[90:91] op_sel_hi:[1,0,1]
	v_cvt_pk_f32_fp8_e32 v[90:91], v100
	v_pk_fma_f32 v[90:91], v[90:91], v[152:153], v[86:87] op_sel_hi:[1,0,1]
	v_cvt_pk_f32_fp8_sdwa v[86:87], v100 src0_sel:WORD_1
	v_pk_fma_f32 v[86:87], v[86:87], v[152:153], v[82:83] op_sel_hi:[1,0,1]
	v_cvt_pk_f32_fp8_e32 v[82:83], v101
	v_cvt_pk_f32_fp8_sdwa v[100:101], v101 src0_sel:WORD_1
	v_pk_fma_f32 v[82:83], v[82:83], v[152:153], v[78:79] op_sel_hi:[1,0,1]
	v_pk_fma_f32 v[150:151], v[100:101], v[152:153], v[150:151] op_sel_hi:[1,0,1]
	v_cvt_pk_f32_fp8_e32 v[100:101], v102
	v_mov_b32_e32 v152, v153
	v_pk_fma_f32 v[100:101], v[100:101], v[152:153], v[92:93] op_sel_hi:[1,0,1]
	v_cvt_pk_f32_fp8_sdwa v[92:93], v102 src0_sel:WORD_1
	v_pk_fma_f32 v[92:93], v[92:93], v[152:153], v[88:89] op_sel_hi:[1,0,1]
	v_cvt_pk_f32_fp8_e32 v[88:89], v103
	v_cvt_pk_f32_fp8_sdwa v[102:103], v103 src0_sel:WORD_1
	v_pk_fma_f32 v[88:89], v[88:89], v[152:153], v[84:85] op_sel_hi:[1,0,1]
	v_pk_fma_f32 v[102:103], v[102:103], v[152:153], v[98:99] op_sel_hi:[1,0,1]
	v_cvt_pk_f32_fp8_e32 v[98:99], v104
	v_pk_fma_f32 v[98:99], v[98:99], v[152:153], v[90:91] op_sel_hi:[1,0,1]
	v_cvt_pk_f32_fp8_sdwa v[90:91], v104 src0_sel:WORD_1
	v_pk_fma_f32 v[90:91], v[90:91], v[152:153], v[86:87] op_sel_hi:[1,0,1]
	v_cvt_pk_f32_fp8_e32 v[86:87], v105
	v_cvt_pk_f32_fp8_sdwa v[104:105], v105 src0_sel:WORD_1
	v_pk_fma_f32 v[86:87], v[86:87], v[152:153], v[82:83] op_sel_hi:[1,0,1]
	v_pk_fma_f32 v[104:105], v[104:105], v[152:153], v[150:151] op_sel_hi:[1,0,1]
	v_cvt_pk_f32_fp8_e32 v[150:151], v106
	v_cvt_pk_f32_fp8_sdwa v[152:153], v106 src0_sel:WORD_1
	v_pk_fma_f32 v[150:151], v[150:151], v[146:147], v[100:101] op_sel_hi:[1,0,1]
	v_cvt_pk_f32_fp8_e32 v[100:101], v107
	v_cvt_pk_f32_fp8_sdwa v[106:107], v107 src0_sel:WORD_1
	v_pk_fma_f32 v[152:153], v[152:153], v[146:147], v[92:93] op_sel_hi:[1,0,1]
	v_pk_fma_f32 v[100:101], v[100:101], v[146:147], v[88:89] op_sel_hi:[1,0,1]
	v_pk_fma_f32 v[106:107], v[106:107], v[146:147], v[102:103] op_sel_hi:[1,0,1]
	v_cvt_pk_f32_fp8_e32 v[102:103], v108
	v_pk_fma_f32 v[102:103], v[102:103], v[146:147], v[98:99] op_sel_hi:[1,0,1]
	v_cvt_pk_f32_fp8_sdwa v[98:99], v108 src0_sel:WORD_1
	v_pk_fma_f32 v[98:99], v[98:99], v[146:147], v[90:91] op_sel_hi:[1,0,1]
	v_cvt_pk_f32_fp8_e32 v[90:91], v109
	v_cvt_pk_f32_fp8_sdwa v[108:109], v109 src0_sel:WORD_1
	v_pk_fma_f32 v[90:91], v[90:91], v[146:147], v[86:87] op_sel_hi:[1,0,1]
	v_pk_fma_f32 v[108:109], v[108:109], v[146:147], v[104:105] op_sel_hi:[1,0,1]
	v_cvt_pk_f32_fp8_e32 v[104:105], v110
	v_pk_fma_f32 v[104:105], v[104:105], v[146:147], v[150:151] op_sel:[0,1,0]
	v_cvt_pk_f32_fp8_sdwa v[150:151], v110 src0_sel:WORD_1
	v_pk_fma_f32 v[150:151], v[150:151], v[146:147], v[152:153] op_sel:[0,1,0]
	v_cvt_pk_f32_fp8_e32 v[152:153], v111
	v_cvt_pk_f32_fp8_sdwa v[110:111], v111 src0_sel:WORD_1
	v_pk_fma_f32 v[152:153], v[152:153], v[146:147], v[100:101] op_sel:[0,1,0]
	v_pk_fma_f32 v[110:111], v[110:111], v[146:147], v[106:107] op_sel:[0,1,0]
; __device__ __forceinline__ f32x2 fp8x2_lo(unsigned w) { return __builtin_amdgcn_cvt_pk_f32_fp8(w, false); }
; __device__ __forceinline__ f32x2 fp8x2_hi(unsigned w) { return __builtin_amdgcn_cvt_pk_f32_fp8(w, true); }
; template <bool NT>
; __device__ __forceinline__ void peer_passB(const Args& a, const PeerWork w) {
;     ...
;         for (int k = 0; k < 16; ++k) {
;             const unsigned ww[4] = {vr[k].x, vr[k].y, vr[k].z, vr[k].w};
;             const float c = cf[k >> 2][k & 3]; const f32x2 c2 = {c, c};
; #pragma unroll
;             for (int wd = 0; wd < 4; ++wd) { acc[2 * wd] = __builtin_elementwise_fma(fp8x2_lo(ww[wd]), c2, acc[2 * wd]); acc[2 * wd + 1] = __builtin_elementwise_fma(fp8x2_hi(ww[wd]), c2, acc[2 * wd + 1]); }
	v_cvt_pk_f32_fp8_e32 v[106:107], v112
	v_pk_fma_f32 v[106:107], v[106:107], v[146:147], v[102:103] op_sel:[0,1,0]
	v_cvt_pk_f32_fp8_sdwa v[102:103], v112 src0_sel:WORD_1
	v_pk_fma_f32 v[102:103], v[102:103], v[146:147], v[98:99] op_sel:[0,1,0]
	v_cvt_pk_f32_fp8_e32 v[98:99], v113
	v_cvt_pk_f32_fp8_sdwa v[112:113], v113 src0_sel:WORD_1
	v_pk_fma_f32 v[98:99], v[98:99], v[146:147], v[90:91] op_sel:[0,1,0]
	v_pk_fma_f32 v[146:147], v[112:113], v[146:147], v[108:109] op_sel:[0,1,0]
	v_cvt_pk_f32_fp8_e32 v[112:113], v114
	v_cvt_pk_f32_fp8_sdwa v[108:109], v114 src0_sel:WORD_1
	v_pk_fma_f32 v[112:113], v[112:113], v[148:149], v[104:105] op_sel_hi:[1,0,1]
	v_cvt_pk_f32_fp8_e32 v[104:105], v115
	v_cvt_pk_f32_fp8_sdwa v[114:115], v115 src0_sel:WORD_1
	v_pk_fma_f32 v[108:109], v[108:109], v[148:149], v[150:151] op_sel_hi:[1,0,1]
	v_pk_fma_f32 v[104:105], v[104:105], v[148:149], v[152:153] op_sel_hi:[1,0,1]
	v_pk_fma_f32 v[114:115], v[114:115], v[148:149], v[110:111] op_sel_hi:[1,0,1]
	v_cvt_pk_f32_fp8_e32 v[110:111], v116
	v_pk_fma_f32 v[110:111], v[110:111], v[148:149], v[106:107] op_sel_hi:[1,0,1]
	v_cvt_pk_f32_fp8_sdwa v[106:107], v116 src0_sel:WORD_1
	v_pk_fma_f32 v[106:107], v[106:107], v[148:149], v[102:103] op_sel_hi:[1,0,1]
	v_cvt_pk_f32_fp8_e32 v[102:103], v117
	v_cvt_pk_f32_fp8_sdwa v[116:117], v117 src0_sel:WORD_1
	v_pk_fma_f32 v[102:103], v[102:103], v[148:149], v[98:99] op_sel_hi:[1,0,1]
	v_pk_fma_f32 v[146:147], v[116:117], v[148:149], v[146:147] op_sel_hi:[1,0,1]
	v_cvt_pk_f32_fp8_e32 v[116:117], v118
	v_mov_b32_e32 v148, v149
	v_pk_fma_f32 v[116:117], v[116:117], v[148:149], v[112:113] op_sel_hi:[1,0,1]
	v_cvt_pk_f32_fp8_sdwa v[112:113], v118 src0_sel:WORD_1
	v_pk_fma_f32 v[112:113], v[112:113], v[148:149], v[108:109] op_sel_hi:[1,0,1]
	v_cvt_pk_f32_fp8_e32 v[108:109], v119
	v_cvt_pk_f32_fp8_sdwa v[118:119], v119 src0_sel:WORD_1
	v_pk_fma_f32 v[108:109], v[108:109], v[148:149], v[104:105] op_sel_hi:[1,0,1]
	v_pk_fma_f32 v[118:119], v[118:119], v[148:149], v[114:115] op_sel_hi:[1,0,1]
	v_cvt_pk_f32_fp8_e32 v[114:115], v120
	v_pk_fma_f32 v[114:115], v[114:115], v[148:149], v[110:111] op_sel_hi:[1,0,1]
	v_cvt_pk_f32_fp8_sdwa v[110:111], v120 src0_sel:WORD_1
	v_pk_fma_f32 v[110:111], v[110:111], v[148:149], v[106:107] op_sel_hi:[1,0,1]
	v_cvt_pk_f32_fp8_e32 v[106:107], v121
	v_cvt_pk_f32_fp8_sdwa v[120:121], v121 src0_sel:WORD_1
	v_pk_fma_f32 v[106:107], v[106:107], v[148:149], v[102:103] op_sel_hi:[1,0,1]
	v_pk_fma_f32 v[146:147], v[120:121], v[148:149], v[146:147] op_sel_hi:[1,0,1]
	v_cvt_pk_f32_fp8_e32 v[148:149], v122
	v_cvt_pk_f32_fp8_sdwa v[120:121], v122 src0_sel:WORD_1
	v_pk_fma_f32 v[148:149], v[148:149], v[142:143], v[116:117] op_sel_hi:[1,0,1]
	v_cvt_pk_f32_fp8_e32 v[116:117], v123
	v_cvt_pk_f32_fp8_sdwa v[122:123], v123 src0_sel:WORD_1
	v_pk_fma_f32 v[120:121], v[120:121], v[142:143], v[112:113] op_sel_hi:[1,0,1]
	v_pk_fma_f32 v[116:117], v[116:117], v[142:143], v[108:109] op_sel_hi:[1,0,1]
	v_pk_fma_f32 v[122:123], v[122:123], v[142:143], v[118:119] op_sel_hi:[1,0,1]
	v_cvt_pk_f32_fp8_e32 v[118:119], v124
	v_pk_fma_f32 v[118:119], v[118:119], v[142:143], v[114:115] op_sel_hi:[1,0,1]
	v_cvt_pk_f32_fp8_sdwa v[114:115], v124 src0_sel:WORD_1
	v_pk_fma_f32 v[114:115], v[114:115], v[142:143], v[110:111] op_sel_hi:[1,0,1]
	v_cvt_pk_f32_fp8_e32 v[110:111], v125
	v_cvt_pk_f32_fp8_sdwa v[124:125], v125 src0_sel:WORD_1
	v_pk_fma_f32 v[110:111], v[110:111], v[142:143], v[106:107] op_sel_hi:[1,0,1]
	v_pk_fma_f32 v[124:125], v[124:125], v[142:143], v[146:147] op_sel_hi:[1,0,1]
	v_cvt_pk_f32_fp8_e32 v[146:147], v126
	v_pk_fma_f32 v[146:147], v[146:147], v[142:143], v[148:149] op_sel:[0,1,0]
	v_cvt_pk_f32_fp8_sdwa v[148:149], v126 src0_sel:WORD_1
	v_pk_fma_f32 v[148:149], v[148:149], v[142:143], v[120:121] op_sel:[0,1,0]
	v_cvt_pk_f32_fp8_e32 v[120:121], v127
	v_cvt_pk_f32_fp8_sdwa v[126:127], v127 src0_sel:WORD_1
	v_pk_fma_f32 v[120:121], v[120:121], v[142:143], v[116:117] op_sel:[0,1,0]
	v_pk_fma_f32 v[126:127], v[126:127], v[142:143], v[122:123] op_sel:[0,1,0]
; template <int CTRL> __device__ __forceinline__ float dpp_f(float x) { return __uint_as_float((unsigned)__builtin_amdgcn_update_dpp(0, (int)__float_as_uint(x), CTRL, 0xf, 0xf, false)); }
; template <bool NT>
; __device__ __forceinline__ void peer_passB(const Args& a, const PeerWork w) {
;     ...
;         float w8[8], w4[4], w2[2];
; #pragma unroll
;         for (int m = 0; m < 8; ++m) { const auto sw = __builtin_amdgcn_permlane32_swap(__float_as_uint(acc[m >> 1][m & 1]), __float_as_uint(acc[(m + 8) >> 1][m & 1]), false, false); w8[m] = __uint_as_float(sw[0]) + __uint_as_float(sw[1]); }
; #pragma unroll
;         for (int m = 0; m < 4; ++m) { const auto sw = __builtin_amdgcn_permlane16_swap(__float_as_uint(w8[m]), __float_as_uint(w8[m + 4]), false, false); w4[m] = __uint_as_float(sw[0]) + __uint_as_float(sw[1]); }
;         { const bool up = (lane & 8) != 0;
; #pragma unroll
;           for (int m = 0; m < 2; ++m) { const float keep = up ? w4[m + 2] : w4[m], send = up ? w4[m] : w4[m + 2]; w2[m] = keep + dpp_f<0x128>(send); } }
;         *(f32x2*)(Y + (size_t)t * DM) = (f32x2){hv[0] + w2[0], hv[1] + w2[1]};
;         if (q + qs > ql) break;
; #pragma unroll
;         for (int k = 0; k < 16; ++k) vr[k] = vrn[k];
; #pragma unroll
;         for (int qq = 0; qq < 4; ++qq) cf[qq] = cfn[qq];
;         hv = hn;
;         t = t1; t1 = t2;
;     }
	v_cvt_pk_f32_fp8_e32 v[122:123], v128
	v_pk_fma_f32 v[122:123], v[122:123], v[142:143], v[118:119] op_sel:[0,1,0]
	v_cvt_pk_f32_fp8_sdwa v[118:119], v128 src0_sel:WORD_1
	v_pk_fma_f32 v[118:119], v[118:119], v[142:143], v[114:115] op_sel:[0,1,0]
	v_cvt_pk_f32_fp8_e32 v[114:115], v129
	v_cvt_pk_f32_fp8_sdwa v[128:129], v129 src0_sel:WORD_1
	v_pk_fma_f32 v[114:115], v[114:115], v[142:143], v[110:111] op_sel:[0,1,0]
	v_pk_fma_f32 v[142:143], v[128:129], v[142:143], v[124:125] op_sel:[0,1,0]
	v_cvt_pk_f32_fp8_e32 v[128:129], v130
	v_cvt_pk_f32_fp8_sdwa v[124:125], v130 src0_sel:WORD_1
	v_pk_fma_f32 v[128:129], v[128:129], v[144:145], v[146:147] op_sel_hi:[1,0,1]
	v_cvt_pk_f32_fp8_e32 v[146:147], v131
	v_cvt_pk_f32_fp8_sdwa v[130:131], v131 src0_sel:WORD_1
	v_pk_fma_f32 v[124:125], v[124:125], v[144:145], v[148:149] op_sel_hi:[1,0,1]
	v_cvt_pk_f32_fp8_e32 v[148:149], v133
	v_pk_fma_f32 v[146:147], v[146:147], v[144:145], v[120:121] op_sel_hi:[1,0,1]
	v_pk_fma_f32 v[130:131], v[130:131], v[144:145], v[126:127] op_sel_hi:[1,0,1]
	v_cvt_pk_f32_fp8_e32 v[126:127], v132
	v_pk_fma_f32 v[148:149], v[148:149], v[144:145], v[114:115] op_sel_hi:[1,0,1]
	v_pk_fma_f32 v[126:127], v[126:127], v[144:145], v[122:123] op_sel_hi:[1,0,1]
	v_cvt_pk_f32_fp8_sdwa v[122:123], v132 src0_sel:WORD_1
	v_cvt_pk_f32_fp8_sdwa v[132:133], v133 src0_sel:WORD_1
	v_pk_fma_f32 v[122:123], v[122:123], v[144:145], v[118:119] op_sel_hi:[1,0,1]
	v_pk_fma_f32 v[142:143], v[132:133], v[144:145], v[142:143] op_sel_hi:[1,0,1]
	v_cvt_pk_f32_fp8_e32 v[132:133], v134
	v_mov_b32_e32 v144, v145
	v_pk_fma_f32 v[132:133], v[132:133], v[144:145], v[128:129] op_sel_hi:[1,0,1]
	v_cvt_pk_f32_fp8_sdwa v[128:129], v134 src0_sel:WORD_1
	v_pk_fma_f32 v[128:129], v[128:129], v[144:145], v[124:125] op_sel_hi:[1,0,1]
	v_cvt_pk_f32_fp8_e32 v[124:125], v135
	v_cvt_pk_f32_fp8_sdwa v[134:135], v135 src0_sel:WORD_1
	v_pk_fma_f32 v[124:125], v[124:125], v[144:145], v[146:147] op_sel_hi:[1,0,1]
	v_pk_fma_f32 v[134:135], v[134:135], v[144:145], v[130:131] op_sel_hi:[1,0,1]
	v_cvt_pk_f32_fp8_e32 v[130:131], v136
	v_pk_fma_f32 v[130:131], v[130:131], v[144:145], v[126:127] op_sel_hi:[1,0,1]
	v_cvt_pk_f32_fp8_sdwa v[126:127], v136 src0_sel:WORD_1
	s_nop 0
	v_permlane32_swap_b32_e32 v132, v130
	v_permlane32_swap_b32_e32 v133, v131
	v_pk_fma_f32 v[126:127], v[126:127], v[144:145], v[122:123] op_sel_hi:[1,0,1]
	v_cvt_pk_f32_fp8_e32 v[122:123], v137
	v_cvt_pk_f32_fp8_sdwa v[136:137], v137 src0_sel:WORD_1
	v_permlane32_swap_b32_e32 v128, v126
	v_pk_fma_f32 v[122:123], v[122:123], v[144:145], v[148:149] op_sel_hi:[1,0,1]
	v_pk_fma_f32 v[136:137], v[136:137], v[144:145], v[142:143] op_sel_hi:[1,0,1]
	v_permlane32_swap_b32_e32 v129, v127
	v_permlane32_swap_b32_e32 v124, v122
	v_permlane32_swap_b32_e32 v125, v123
	v_permlane32_swap_b32_e32 v134, v136
	v_permlane32_swap_b32_e32 v135, v137
	v_add_f32_e32 v142, v132, v130
	v_add_f32_e32 v143, v133, v131
	v_add_f32_e32 v144, v128, v126
	v_add_f32_e32 v145, v129, v127
	v_add_f32_e32 v130, v124, v122
	v_add_f32_e32 v131, v125, v123
	v_add_f32_e32 v134, v134, v136
	v_add_f32_e32 v135, v135, v137
	v_permlane16_swap_b32_e32 v142, v130
	v_permlane16_swap_b32_e32 v143, v131
	v_permlane16_swap_b32_e32 v144, v134
	v_permlane16_swap_b32_e32 v145, v135
	v_pk_add_f32 v[136:137], v[142:143], v[130:131]
	v_pk_add_f32 v[134:135], v[144:145], v[134:135]
	v_mov_b32_e32 v142, 0
	v_cndmask_b32_e32 v143, v136, v134, vcc
	v_cndmask_b32_e32 v144, v134, v136, vcc
	v_cndmask_b32_e32 v134, v137, v135, vcc
	v_mov_b32_dpp v142, v143 row_ror:8 row_mask:0xf bank_mask:0xf
	v_mov_b32_e32 v143, 0
	v_cndmask_b32_e32 v145, v135, v137, vcc
	v_lshl_add_u64 v[136:137], v[186:187], 0, s[12:13]
	v_mov_b32_dpp v143, v134 row_ror:8 row_mask:0xf bank_mask:0xf
	v_pk_add_f32 v[134:135], v[144:145], v[142:143]
	v_pk_add_f32 v[134:135], v[188:189], v[134:135]
	global_store_dwordx2 v[136:137], v[134:135], off
	s_mov_b32 s12, s14
	s_cbranch_scc1 .LBB0_1587
	s_waitcnt vmcnt(0)
